# static s_setprio 1 for waves 0-3 during GEMM phases (no per-phase flips)
# speedup vs baseline: 1.0329x; 1.0024x over previous
; #define PG8_STAGE(bufoff, gbase, voff) do { _Pragma("unroll") for (int _i = 0; _i < 2; ++_i) \
;         __builtin_amdgcn_global_load_lds((const unsigned*)((const char*)(gbase) + (voff)[_i]), (LAS unsigned*)(lds + (bufoff) + ldsw + _i * 8192), 16, 0, 0); } while (0)
; #define PG8_BAR __builtin_amdgcn_s_barrier()
; template <class Epi>
; __device__ __forceinline__ void gemm_phase(LAS unsigned char* lds, const Gemm g, const StaticOrder& S, const Epi& E) {
;     int tid = threadIdx.x; asm volatile("" : "+v"(tid));
;     const int wid = __builtin_amdgcn_readfirstlane(tid >> 6), lane = tid & 63, wr = wid >> 2, wc = wid & 3, fr = lane & 15, fq = lane >> 4;
;     const int K = g.K, nt = K / BK;
;     unsigned voffA[2], voffB0[2], voffB1[2];
; #pragma unroll
;     for (int i = 0; i < 2; ++i) { int R, C; stage_rc(tid * 16 + i * 8192, R, C);
;         const int Rw = 64 * (R >> 5) + 16 * ((R >> 2) & 3) + 4 * ((R >> 4) & 1) + (R & 3);
;         const int Rf = 64 * (R >> 5) + 8 * ((R >> 2) & 3) + 4 * ((R >> 4) & 1) + (R & 3);
;         const int Rb0 = Epi::PERM ? (Epi::F32OUT ? Rf : Rw) : R, Rb1 = Epi::PERM ? (Epi::F32OUT ? Rf + 32 : Rw + 8) : R + HALF;
;         voffA[i] = (unsigned)(R * K + C) * 2u; voffB0[i] = (unsigned)(Rb0 * K + C) * 2u; voffB1[i] = (unsigned)(Rb1 * K + C) * 2u; }
;     const size_t kstep = (size_t)(BK * 2);
;     const size_t hstep = (size_t)HALF * K * 2;
;     const size_t tstep = 2 * hstep;
;     const unsigned ldsw = (unsigned)wid * 1024u;
;     const int aoff = lds_byte(wr * 64 + fr, fq * 8), boff = lds_byte(wc * 32 + fr, fq * 8);
;     ...
;     Unit cur, nxt; int ui = 0;
;     if (!S.next(0, cur)) return;
;     f32x4 acc[2][2][4][2];
; #pragma unroll
;     for (int a = 0; a < 2; ++a)
; #pragma unroll
;         for (int b = 0; b < 2; ++b)
; #pragma unroll
;             for (int m = 0; m < 4; ++m)
; #pragma unroll
;                 for (int n = 0; n < 2; ++n) acc[a][b][m][n] = (f32x4){0.f, 0.f, 0.f, 0.f};
;     bf16x8 At[4][2], B0[2][2], B1[2][2];
;     const char* cA = (const char*)g.A + (size_t)cur.pm * tstep; const char* cB = (const char*)g.Bt + (size_t)cur.pn * tstep;
;     PG8_STAGE(PG8_SB(0, 0), cB, voffB0); PG8_STAGE(PG8_SA(0, 0), cA, voffA); PG8_STAGE(PG8_SB(0, 1), cB, voffB1); PG8_STAGE(PG8_SA(0, 1), cA + hstep, voffA);
;     if (wr == 1) PG8_BAR;
.LBB0_99:
	s_or_b64 exec, exec, s[4:5]
	s_mov_b64 s[4:5], s[0:1]
	s_waitcnt lgkmcnt(0)
	v_mov_b32_e32 v0, v202
	s_mov_b32 s6, s2
	v_mov_b32_e32 v12, v202
	s_barrier
	s_cmpk_gt_i32 s2, 0x3ff
	v_readfirstlane_b32 s27, v12
	s_cbranch_scc1 .LBB0_112
	v_lshlrev_b32_e32 v0, 4, v12
	v_add_u32_e32 v1, 0x2000, v0
	v_ashrrev_i32_e32 v2, 31, v1
	v_lshrrev_b32_e32 v2, 22, v2
	v_add_u32_e32 v2, v1, v2
	v_ashrrev_i32_e32 v13, 10, v2
	v_mul_i32_i24_e32 v2, 0x400, v13
	v_sub_u32_e32 v1, v1, v2
	v_lshrrev_b32_e32 v2, 4, v1
	v_bitop3_b32 v1, v2, v1, 32 bitop3:0x6c
	v_ashrrev_i32_e32 v2, 31, v1
	v_lshrrev_b32_e32 v2, 26, v2
	v_add_u32_e32 v2, v1, v2
	v_lshlrev_b32_e32 v3, 3, v13
	v_ashrrev_i32_e32 v14, 6, v2
	v_and_b32_e32 v3, -16, v3
	s_load_dwordx2 s[4:5], s[4:5], 0xf0
	v_add_u32_e32 v3, v14, v3
	v_lshlrev_b32_e32 v4, 2, v3
	v_and_b32_e32 v5, 3, v14
	v_and_or_b32 v4, v4, 48, v5
	v_lshlrev_b32_e32 v5, 1, v3
	v_lshrrev_b32_e32 v6, 2, v3
	v_and_b32_e32 v2, 0xc0, v2
	v_and_b32_e32 v5, 0xfffc0, v5
	v_and_b32_e32 v6, 4, v6
	v_sub_u32_e32 v1, v1, v2
	v_mov_b32_e32 v2, 1
	v_or3_b32 v4, v4, v5, v6
	v_lshlrev_b32_e32 v5, 5, v13
	v_ashrrev_i16_sdwa v1, v2, sext(v1) dst_sel:DWORD dst_unused:UNUSED_PAD src0_sel:DWORD src1_sel:BYTE_0
	s_waitcnt lgkmcnt(0)
	s_add_u32 s40, s4, 0x6400000
	v_and_b32_e32 v5, 32, v5
	v_bfe_i32 v15, v1, 0, 16
	s_addc_u32 s41, s5, 0
	v_add_lshl_u32 v1, v5, v15, 1
	s_add_u32 s42, s4, 0x4900000
	v_lshl_add_u32 v128, v4, 12, v1
	v_lshl_add_u32 v132, v3, 12, v1
	v_bfe_i32 v1, v12, 27, 1
	s_addc_u32 s43, s5, 0
	v_lshrrev_b32_e32 v1, 22, v1
	s_ashr_i32 s45, s2, 31
	v_add_u32_e32 v1, v0, v1
	s_lshr_b32 s6, s45, 29
	v_and_b32_e32 v1, 0xfffffc00, v1
	s_add_i32 s6, s2, s6
	v_sub_u32_e32 v0, v0, v1
	s_ashr_i32 s7, s6, 3
	s_and_b32 s6, s6, -8
	v_lshrrev_b32_e32 v1, 4, v0
	v_ashrrev_i32_e32 v3, 31, v12
	s_sub_i32 s6, s2, s6
	v_bitop3_b32 v0, v1, v0, 32 bitop3:0x6c
	v_lshrrev_b32_e32 v3, 26, v3
	s_lshr_b32 s8, s6, 31
	v_ashrrev_i32_e32 v1, 31, v0
	v_add_u32_e32 v3, v12, v3
	s_bitset1_b32 s8, 7
	v_lshrrev_b32_e32 v1, 26, v1
	v_ashrrev_i32_e32 v17, 6, v3
	s_mul_i32 s6, s8, s6
	v_add_u32_e32 v1, v0, v1
	v_lshlrev_b32_e32 v3, 3, v17
	s_add_i32 s6, s6, s7
	v_ashrrev_i32_e32 v16, 6, v1
	v_and_b32_e32 v3, -16, v3
	s_ashr_i32 s7, s6, 31
	v_add_u32_e32 v3, v16, v3
	s_lshr_b32 s7, s7, 25
	v_lshlrev_b32_e32 v4, 2, v3
	v_and_b32_e32 v5, 3, v16
	s_add_i32 s7, s6, s7
	v_and_or_b32 v4, v4, 48, v5
	v_lshlrev_b32_e32 v5, 1, v3
	v_lshrrev_b32_e32 v6, 2, v3
	v_and_b32_e32 v1, 0xc0, v1
	s_ashr_i32 s7, s7, 7
	v_and_b32_e32 v5, 0xfffc0, v5
	v_and_b32_e32 v6, 4, v6
	v_sub_u32_e32 v0, v0, v1
	s_lshl_b32 s8, s7, 3
	v_or3_b32 v4, v4, v5, v6
	v_lshlrev_b32_e32 v5, 5, v17
	v_ashrrev_i16_sdwa v0, v2, sext(v0) dst_sel:DWORD dst_unused:UNUSED_PAD src0_sel:DWORD src1_sel:BYTE_0
	s_sub_i32 s9, 64, s8
	s_lshl_b32 s7, s7, 7
	v_and_b32_e32 v5, 32, v5
	v_bfe_i32 v18, v0, 0, 16
	s_min_u32 s9, s9, 8
	s_sub_i32 s13, s6, s7
	v_add_lshl_u32 v0, v5, v18, 1
	s_sext_i32_i8 s6, s13
	v_cvt_f32_ubyte0_e32 v2, s9
	v_lshl_add_u32 v134, v4, 12, v0
	v_cvt_f32_i32_e32 v1, s6
	v_rcp_iflag_f32_e32 v4, v2
	v_lshl_add_u32 v138, v3, 12, v0
	s_ashr_i32 s12, s27, 6
	s_ashr_i32 s6, s6, 30
	v_mul_f32_e32 v0, v1, v4
	v_trunc_f32_e32 v0, v0
	v_fma_f32 v1, -v0, v2, v1
	v_cvt_i32_f32_e32 v0, v0
	s_ashr_i32 s11, s27, 8
	s_lshl_b32 s44, s12, 10
	s_or_b32 s10, s6, 1
	v_cmp_ge_f32_e64 s[6:7], |v1|, v2
	s_and_b64 s[6:7], s[6:7], exec
	s_cselect_b32 s6, s10, 0
	v_readfirstlane_b32 s7, v0
	s_add_i32 s10, s7, s6
	s_mul_i32 s6, s10, s9
	s_sub_i32 s6, s13, s6
	s_sext_i32_i8 s6, s6
	s_add_i32 s30, s8, s6
	s_ashr_i32 s31, s30, 31
	s_bfe_i64 s[8:9], s[10:11], 0x80000
	s_lshl_b64 s[6:7], s[30:31], 20
	s_lshl_b64 s[8:9], s[8:9], 20
	s_add_u32 s36, s42, s8
	s_addc_u32 s37, s43, s9
	s_add_i32 s31, s44, 0
	s_add_i32 m0, s31, 0x10000
	v_add_u32_e32 v136, 0x8000, v134
	global_load_lds_dwordx4 v134, s[36:37]
	s_add_i32 m0, s31, 0x12000
	s_add_u32 s34, s40, s6
	global_load_lds_dwordx4 v128, s[36:37]
	s_addc_u32 s35, s41, s7
	s_mov_b32 m0, s31
	s_add_i32 s46, s31, 0x2000
	global_load_lds_dwordx4 v138, s[34:35]
	s_mov_b32 m0, s46
	v_add_u32_e32 v130, 0x8000, v128
	global_load_lds_dwordx4 v132, s[34:35]
	s_add_i32 m0, s31, 0x14000
	v_mov_b32_e32 v135, 0
	global_load_lds_dwordx4 v136, s[36:37]
	s_add_i32 m0, s31, 0x16000
	s_add_u32 s6, s34, 0x80000
	s_addc_u32 s7, s35, 0
	s_add_i32 s47, s31, 0x4000
	global_load_lds_dwordx4 v130, s[36:37]
	s_mov_b32 m0, s47
	s_add_i32 s48, s31, 0x6000
	global_load_lds_dwordx4 v138, s[6:7]
	s_mov_b32 m0, s48
	v_mov_b32_e32 v129, v135
	global_load_lds_dwordx4 v132, s[6:7]
	v_mov_b32_e32 v139, v135
	v_mov_b32_e32 v133, v135
	v_mov_b32_e32 v137, v135
	v_mov_b32_e32 v131, v135
	s_mov_b32 s50, 0
	s_mov_b32 s49, 0x10000
	v_lshl_add_u64 v[10:11], s[36:37], 0, v[134:135]
	v_lshl_add_u64 v[8:9], s[36:37], 0, v[128:129]
	v_lshl_add_u64 v[6:7], s[34:35], 0, v[138:139]
	v_lshl_add_u64 v[4:5], s[34:35], 0, v[132:133]
	v_lshl_add_u64 v[0:1], s[36:37], 0, v[136:137]
	s_cmp_lg_u32 s11, 1
	v_lshl_add_u64 v[2:3], s[36:37], 0, v[130:131]
	s_setprio 1
	s_cbranch_scc1 .LBB0_102
	s_barrier
	s_setprio 0

; #define PG8_WAIT_V(n) asm volatile("s_waitcnt vmcnt(" #n ")" ::: "memory")
; #define PG8_BAR __builtin_amdgcn_s_barrier()
; template <class Epi>
; __device__ __forceinline__ void gemm_phase(LAS unsigned char* lds, const Gemm g, const StaticOrder& S, const Epi& E) {
;     ...
;     PG8_WAIT_V(0);
;     if (wr == 0) PG8_BAR;
;     PG8_BAR;
.LBB0_111:
	s_barrier
	s_setprio 0

;     __device__ bool next(int i, Unit& u) const {
;         if (i >= icnt) return false;
;         const long L = (long)(i + ioff) * G + c; if (L >= nwg) return false;
; template <class Epi>
; __device__ __forceinline__ void gemm_phase(LAS unsigned char* lds, const Gemm g, const StaticOrder& S, const Epi& E) {
;     int tid = threadIdx.x; asm volatile("" : "+v"(tid));
;     const int wid = __builtin_amdgcn_readfirstlane(tid >> 6), lane = tid & 63, wr = wid >> 2, wc = wid & 3, fr = lane & 15, fq = lane >> 4;
;     const int K = g.K, nt = K / BK;
;     unsigned voffA[2], voffB0[2], voffB1[2];
; #pragma unroll
;     for (int i = 0; i < 2; ++i) { int R, C; stage_rc(tid * 16 + i * 8192, R, C);
;         const int Rw = 64 * (R >> 5) + 16 * ((R >> 2) & 3) + 4 * ((R >> 4) & 1) + (R & 3);
;         const int Rf = 64 * (R >> 5) + 8 * ((R >> 2) & 3) + 4 * ((R >> 4) & 1) + (R & 3);
;         const int Rb0 = Epi::PERM ? (Epi::F32OUT ? Rf : Rw) : R, Rb1 = Epi::PERM ? (Epi::F32OUT ? Rf + 32 : Rw + 8) : R + HALF;
;         voffA[i] = (unsigned)(R * K + C) * 2u; voffB0[i] = (unsigned)(Rb0 * K + C) * 2u; voffB1[i] = (unsigned)(Rb1 * K + C) * 2u; }
;     const size_t kstep = (size_t)(BK * 2);
;     const size_t hstep = (size_t)HALF * K * 2;
;     const size_t tstep = 2 * hstep;
;     const unsigned ldsw = (unsigned)wid * 1024u;
;     const int aoff = lds_byte(wr * 64 + fr, fq * 8), boff = lds_byte(wc * 32 + fr, fq * 8);
;     ...
;     Unit cur, nxt; int ui = 0;
;     if (!S.next(0, cur)) return;
;     f32x4 acc[2][2][4][2];
; #pragma unroll
;     for (int a = 0; a < 2; ++a)
; #pragma unroll
;         for (int b = 0; b < 2; ++b)
; #pragma unroll
;             for (int m = 0; m < 4; ++m)
; #pragma unroll
;                 for (int n = 0; n < 2; ++n) acc[a][b][m][n] = (f32x4){0.f, 0.f, 0.f, 0.f};
;     bf16x8 At[4][2], B0[2][2], B1[2][2];
;     const char* cA = (const char*)g.A + (size_t)cur.pm * tstep; const char* cB = (const char*)g.Bt + (size_t)cur.pn * tstep;
;     PG8_STAGE(PG8_SB(0, 0), cB, voffB0); PG8_STAGE(PG8_SA(0, 0), cA, voffA); PG8_STAGE(PG8_SB(0, 1), cB, voffB1); PG8_STAGE(PG8_SA(0, 1), cA + hstep, voffA);
;     if (wr == 1) PG8_BAR;
;     PG8_WAIT_V(4); PG8_BAR;
;     PG8_STAGE(PG8_SB(1, 0), cB + kstep, voffB0); PG8_STAGE(PG8_SA(1, 0), cA + kstep, voffA); PG8_STAGE(PG8_SB(1, 1), cB + kstep, voffB1);
;     PG8_WAIT_V(6); PG8_BAR;
.LBB0_226:
	s_or_b64 exec, exec, s[4:5]
	s_mov_b64 s[4:5], s[0:1]
	s_waitcnt lgkmcnt(0)
	v_mov_b32_e32 v0, v202
	s_mov_b32 s6, s2
	v_mov_b32_e32 v12, v202
	s_barrier
	s_cmpk_gt_i32 s2, 0x17f
	v_readfirstlane_b32 s44, v12
	s_cbranch_scc1 .LBB0_239
	v_lshlrev_b32_e32 v0, 4, v12
	v_add_u32_e32 v1, 0x2000, v0
	v_ashrrev_i32_e32 v2, 31, v1
	v_lshrrev_b32_e32 v2, 22, v2
	v_add_u32_e32 v2, v1, v2
	v_ashrrev_i32_e32 v13, 10, v2
	v_mul_i32_i24_e32 v2, 0x400, v13
	v_sub_u32_e32 v1, v1, v2
	v_lshrrev_b32_e32 v2, 4, v1
	v_bitop3_b32 v1, v2, v1, 32 bitop3:0x6c
	v_ashrrev_i32_e32 v2, 31, v1
	v_lshrrev_b32_e32 v2, 26, v2
	v_add_u32_e32 v2, v1, v2
	v_lshlrev_b32_e32 v3, 3, v13
	v_ashrrev_i32_e32 v14, 6, v2
	v_and_b32_e32 v3, -16, v3
	v_add_u32_e32 v3, v14, v3
	s_load_dwordx2 s[4:5], s[4:5], 0xf0
	v_lshlrev_b32_e32 v4, 2, v3
	v_and_b32_e32 v5, 3, v14
	v_and_or_b32 v4, v4, 48, v5
	v_lshlrev_b32_e32 v5, 1, v3
	v_lshrrev_b32_e32 v6, 2, v3
	v_and_b32_e32 v2, 0xc0, v2
	v_and_b32_e32 v5, 0x3fffc0, v5
	v_and_b32_e32 v6, 4, v6
	v_sub_u32_e32 v1, v1, v2
	v_mov_b32_e32 v2, 1
	v_or3_b32 v4, v4, v5, v6
	v_lshlrev_b32_e32 v5, 5, v13
	v_ashrrev_i16_sdwa v1, v2, sext(v1) dst_sel:DWORD dst_unused:UNUSED_PAD src0_sel:DWORD src1_sel:BYTE_0
	v_and_b32_e32 v5, 32, v5
	v_bfe_i32 v15, v1, 0, 16
	s_waitcnt lgkmcnt(0)
	s_add_u32 s45, s4, 0x1cc00000
	v_add_lshl_u32 v1, v5, v15, 1
	s_addc_u32 s46, s5, 0
	v_lshl_add_u32 v128, v4, 10, v1
	v_lshl_add_u32 v132, v3, 10, v1
	v_bfe_i32 v1, v12, 27, 1
	s_add_u32 s47, s4, 0x5900000
	v_lshrrev_b32_e32 v1, 22, v1
	s_addc_u32 s48, s5, 0
	v_add_u32_e32 v1, v0, v1
	s_ashr_i32 s50, s2, 31
	v_and_b32_e32 v1, 0xfffffc00, v1
	s_lshr_b32 s6, s50, 29
	v_sub_u32_e32 v0, v0, v1
	s_add_i32 s6, s2, s6
	v_lshrrev_b32_e32 v1, 4, v0
	v_ashrrev_i32_e32 v3, 31, v12
	s_ashr_i32 s7, s6, 3
	s_and_b32 s6, s6, -8
	v_bitop3_b32 v0, v1, v0, 32 bitop3:0x6c
	v_lshrrev_b32_e32 v3, 26, v3
	s_sub_i32 s6, s2, s6
	v_ashrrev_i32_e32 v1, 31, v0
	v_add_u32_e32 v3, v12, v3
	s_lshr_b32 s8, s6, 31
	v_lshrrev_b32_e32 v1, 26, v1
	v_ashrrev_i32_e32 v17, 6, v3
	s_or_b32 s8, s8, 48
	v_add_u32_e32 v1, v0, v1
	v_lshlrev_b32_e32 v3, 3, v17
	s_mul_i32 s6, s8, s6
	v_ashrrev_i32_e32 v16, 6, v1
	v_and_b32_e32 v3, -16, v3
	s_add_i32 s6, s6, s7
	v_add_u32_e32 v3, v16, v3
	s_mul_hi_i32 s7, s6, 0x2aaaaaab
	v_lshlrev_b32_e32 v4, 2, v3
	v_and_b32_e32 v5, 3, v16
	s_lshr_b32 s8, s7, 31
	s_ashr_i32 s7, s7, 3
	v_and_or_b32 v4, v4, 48, v5
	v_lshlrev_b32_e32 v5, 1, v3
	v_lshrrev_b32_e32 v6, 2, v3
	v_and_b32_e32 v1, 0xc0, v1
	s_add_i32 s7, s7, s8
	v_and_b32_e32 v5, 0x3fffc0, v5
	v_and_b32_e32 v6, 4, v6
	v_sub_u32_e32 v0, v0, v1
	s_lshl_b32 s8, s7, 3
	v_or3_b32 v4, v4, v5, v6
	v_lshlrev_b32_e32 v5, 5, v17
	v_ashrrev_i16_sdwa v0, v2, sext(v0) dst_sel:DWORD dst_unused:UNUSED_PAD src0_sel:DWORD src1_sel:BYTE_0
	s_sub_i32 s9, 64, s8
	s_mul_i32 s7, s7, 48
	v_and_b32_e32 v5, 32, v5
	v_bfe_i32 v18, v0, 0, 16
	s_min_u32 s9, s9, 8
	s_sub_i32 s17, s6, s7
	v_add_lshl_u32 v0, v5, v18, 1
	s_sext_i32_i8 s6, s17
	v_cvt_f32_ubyte0_e32 v2, s9
	v_lshl_add_u32 v134, v4, 10, v0
	v_cvt_f32_i32_e32 v1, s6
	v_rcp_iflag_f32_e32 v4, v2
	v_lshl_add_u32 v138, v3, 10, v0
	s_ashr_i32 s16, s44, 6
	s_ashr_i32 s6, s6, 30
	v_mul_f32_e32 v0, v1, v4
	v_trunc_f32_e32 v0, v0
	v_fma_f32 v1, -v0, v2, v1
	v_cvt_i32_f32_e32 v0, v0
	s_ashr_i32 s11, s44, 8
	s_lshl_b32 s49, s16, 10
	s_or_b32 s10, s6, 1
	v_cmp_ge_f32_e64 s[6:7], |v1|, v2
	s_and_b64 s[6:7], s[6:7], exec
	s_cselect_b32 s6, s10, 0
	v_readfirstlane_b32 s7, v0
	s_add_i32 s10, s7, s6
	s_mul_i32 s6, s10, s9
	s_sub_i32 s6, s17, s6
	s_sext_i32_i8 s6, s6
	s_add_i32 s36, s8, s6
	s_ashr_i32 s37, s36, 31
	s_bfe_i64 s[8:9], s[10:11], 0x80000
	s_lshl_b64 s[6:7], s[36:37], 18
	s_lshl_b64 s[8:9], s[8:9], 18
	s_add_u32 s40, s47, s8
	s_addc_u32 s41, s48, s9
	s_add_i32 s37, s49, 0
	s_add_i32 m0, s37, 0x10000
	v_add_u32_e32 v136, 0x2000, v134
	global_load_lds_dwordx4 v134, s[40:41]
	s_add_i32 m0, s37, 0x12000
	s_add_u32 s38, s45, s6
	global_load_lds_dwordx4 v128, s[40:41]
	s_addc_u32 s39, s46, s7
	s_mov_b32 m0, s37
	s_add_i32 s51, s37, 0x2000
	global_load_lds_dwordx4 v138, s[38:39]
	s_mov_b32 m0, s51
	v_add_u32_e32 v130, 0x2000, v128
	global_load_lds_dwordx4 v132, s[38:39]
	s_add_i32 m0, s37, 0x14000
	v_mov_b32_e32 v135, 0
	global_load_lds_dwordx4 v136, s[40:41]
	s_add_i32 m0, s37, 0x16000
	s_add_u32 s6, s38, 0x20000
	s_addc_u32 s7, s39, 0
	s_add_i32 s52, s37, 0x4000
	global_load_lds_dwordx4 v130, s[40:41]
	s_mov_b32 m0, s52
	s_add_i32 s53, s37, 0x6000
	global_load_lds_dwordx4 v138, s[6:7]
	s_mov_b32 m0, s53
	v_mov_b32_e32 v129, v135
	global_load_lds_dwordx4 v132, s[6:7]
	v_mov_b32_e32 v139, v135
	v_mov_b32_e32 v133, v135
	v_mov_b32_e32 v137, v135
	v_mov_b32_e32 v131, v135
	s_mov_b32 s54, 0
	v_lshl_add_u64 v[10:11], s[40:41], 0, v[134:135]
	v_lshl_add_u64 v[8:9], s[40:41], 0, v[128:129]
	v_lshl_add_u64 v[6:7], s[38:39], 0, v[138:139]
	v_lshl_add_u64 v[4:5], s[38:39], 0, v[132:133]
	v_lshl_add_u64 v[0:1], s[40:41], 0, v[136:137]
	s_cmp_lg_u32 s11, 1
	v_lshl_add_u64 v[2:3], s[40:41], 0, v[130:131]
	s_setprio 1
	s_cbranch_scc1 .LBB0_229
	s_barrier
	s_setprio 0

;     __device__ bool next(int i, Unit& u) const {
;         if (i >= icnt) return false;
;         const long L = (long)(i + ioff) * G + c; if (L >= nwg) return false;
; template <class Epi>
; __device__ __forceinline__ void gemm_phase(LAS unsigned char* lds, const Gemm g, const StaticOrder& S, const Epi& E) {
;     int tid = threadIdx.x; asm volatile("" : "+v"(tid));
;     const int wid = __builtin_amdgcn_readfirstlane(tid >> 6), lane = tid & 63, wr = wid >> 2, wc = wid & 3, fr = lane & 15, fq = lane >> 4;
;     const int K = g.K, nt = K / BK;
;     unsigned voffA[2], voffB0[2], voffB1[2];
; #pragma unroll
;     for (int i = 0; i < 2; ++i) { int R, C; stage_rc(tid * 16 + i * 8192, R, C);
;         const int Rw = 64 * (R >> 5) + 16 * ((R >> 2) & 3) + 4 * ((R >> 4) & 1) + (R & 3);
;         const int Rf = 64 * (R >> 5) + 8 * ((R >> 2) & 3) + 4 * ((R >> 4) & 1) + (R & 3);
;         const int Rb0 = Epi::PERM ? (Epi::F32OUT ? Rf : Rw) : R, Rb1 = Epi::PERM ? (Epi::F32OUT ? Rf + 32 : Rw + 8) : R + HALF;
;         voffA[i] = (unsigned)(R * K + C) * 2u; voffB0[i] = (unsigned)(Rb0 * K + C) * 2u; voffB1[i] = (unsigned)(Rb1 * K + C) * 2u; }
;     const size_t kstep = (size_t)(BK * 2);
;     const size_t hstep = (size_t)HALF * K * 2;
;     const size_t tstep = 2 * hstep;
;     const unsigned ldsw = (unsigned)wid * 1024u;
;     const int aoff = lds_byte(wr * 64 + fr, fq * 8), boff = lds_byte(wc * 32 + fr, fq * 8);
;     ...
;     Unit cur, nxt; int ui = 0;
;     if (!S.next(0, cur)) return;
;     f32x4 acc[2][2][4][2];
; #pragma unroll
;     for (int a = 0; a < 2; ++a)
; #pragma unroll
;         for (int b = 0; b < 2; ++b)
; #pragma unroll
;             for (int m = 0; m < 4; ++m)
; #pragma unroll
;                 for (int n = 0; n < 2; ++n) acc[a][b][m][n] = (f32x4){0.f, 0.f, 0.f, 0.f};
;     bf16x8 At[4][2], B0[2][2], B1[2][2];
;     const char* cA = (const char*)g.A + (size_t)cur.pm * tstep; const char* cB = (const char*)g.Bt + (size_t)cur.pn * tstep;
;     PG8_STAGE(PG8_SB(0, 0), cB, voffB0); PG8_STAGE(PG8_SA(0, 0), cA, voffA); PG8_STAGE(PG8_SB(0, 1), cB, voffB1); PG8_STAGE(PG8_SA(0, 1), cA + hstep, voffA);
;     if (wr == 1) PG8_BAR;
;     PG8_WAIT_V(4); PG8_BAR;
;     PG8_STAGE(PG8_SB(1, 0), cB + kstep, voffB0); PG8_STAGE(PG8_SA(1, 0), cA + kstep, voffA); PG8_STAGE(PG8_SB(1, 1), cB + kstep, voffB1);
;     PG8_WAIT_V(6); PG8_BAR;
.LBB0_239:
	s_mov_b64 s[4:5], s[0:1]
	v_mov_b32_e32 v0, v202
	s_mov_b32 s6, s2
	s_waitcnt vmcnt(0) lgkmcnt(0)
	s_barrier
	s_cmpk_lt_i32 s2, 0x200
	v_mov_b32_e32 v12, v202
	s_cselect_b64 s[6:7], -1, 0
	v_writelane_b32 v252, s6, 0
	s_cmpk_gt_i32 s2, 0x1ff
	v_readfirstlane_b32 s52, v12
	v_writelane_b32 v252, s7, 1
	s_cbranch_scc1 .LBB0_253
	v_lshlrev_b32_e32 v0, 4, v12
	v_add_u32_e32 v1, 0x2000, v0
	v_ashrrev_i32_e32 v2, 31, v1
	v_lshrrev_b32_e32 v2, 22, v2
	v_add_u32_e32 v2, v1, v2
	v_ashrrev_i32_e32 v2, 10, v2
	v_mul_i32_i24_e32 v3, 0x400, v2
	v_sub_u32_e32 v1, v1, v3
	v_lshrrev_b32_e32 v3, 4, v1
	v_bitop3_b32 v1, v3, v1, 32 bitop3:0x6c
	v_ashrrev_i32_e32 v3, 31, v1
	s_load_dwordx2 s[4:5], s[4:5], 0xf0
	v_lshrrev_b32_e32 v3, 26, v3
	v_add_u32_e32 v3, v1, v3
	v_lshlrev_b32_e32 v5, 3, v2
	v_ashrrev_i32_e32 v4, 6, v3
	v_and_b32_e32 v5, -16, v5
	v_add_u32_e32 v5, v4, v5
	v_and_b32_e32 v3, 0xc0, v3
	v_lshlrev_b32_e32 v6, 2, v5
	v_and_b32_e32 v4, 3, v4
	v_sub_u32_e32 v1, v1, v3
	v_mov_b32_e32 v3, 1
	s_waitcnt lgkmcnt(0)
	s_add_u32 s53, s4, 0x1dc00000
	v_and_or_b32 v4, v6, 48, v4
	v_lshlrev_b32_e32 v6, 1, v5
	v_lshrrev_b32_e32 v7, 2, v5
	v_lshlrev_b32_e32 v2, 5, v2
	v_ashrrev_i16_sdwa v1, v3, sext(v1) dst_sel:DWORD dst_unused:UNUSED_PAD src0_sel:DWORD src1_sel:BYTE_0
	s_addc_u32 s54, s5, 0
	v_and_b32_e32 v6, 0x7fffc0, v6
	v_and_b32_e32 v7, 4, v7
	v_and_b32_e32 v2, 32, v2
	v_bfe_i32 v1, v1, 0, 16
	s_add_u32 s55, s4, 0x5a80000
	v_or3_b32 v4, v4, v6, v7
	v_add_lshl_u32 v1, v2, v1, 1
	s_addc_u32 s56, s5, 0
	v_lshl_add_u32 v128, v4, 9, v1
	v_lshl_add_u32 v132, v5, 9, v1
	v_bfe_i32 v1, v12, 27, 1
	s_ashr_i32 s58, s2, 31
	v_lshrrev_b32_e32 v1, 22, v1
	s_lshr_b32 s6, s58, 29
	v_add_u32_e32 v1, v0, v1
	s_add_i32 s6, s2, s6
	v_and_b32_e32 v1, 0xfffffc00, v1
	s_ashr_i32 s7, s6, 3
	s_and_b32 s6, s6, -8
	v_sub_u32_e32 v0, v0, v1
	s_sub_i32 s6, s2, s6
	v_lshrrev_b32_e32 v1, 4, v0
	v_ashrrev_i32_e32 v4, 31, v12
	s_lshr_b32 s8, s6, 31
	v_bitop3_b32 v0, v1, v0, 32 bitop3:0x6c
	v_lshrrev_b32_e32 v4, 26, v4
	s_or_b32 s8, s8, 64
	v_ashrrev_i32_e32 v1, 31, v0
	v_add_u32_e32 v4, v12, v4
	s_mul_i32 s6, s8, s6
	v_lshrrev_b32_e32 v1, 26, v1
	v_ashrrev_i32_e32 v4, 6, v4
	s_add_i32 s6, s6, s7
	v_add_u32_e32 v1, v0, v1
	v_lshlrev_b32_e32 v5, 3, v4
	s_ashr_i32 s7, s6, 31
	v_ashrrev_i32_e32 v2, 6, v1
	v_and_b32_e32 v5, -16, v5
	s_lshr_b32 s7, s7, 26
	v_add_u32_e32 v5, v2, v5
	v_and_b32_e32 v1, 0xc0, v1
	s_add_i32 s7, s6, s7
	v_lshlrev_b32_e32 v6, 2, v5
	v_and_b32_e32 v2, 3, v2
	v_sub_u32_e32 v0, v0, v1
	s_ashr_i32 s7, s7, 6
	v_and_or_b32 v2, v6, 48, v2
	v_lshlrev_b32_e32 v6, 1, v5
	v_lshrrev_b32_e32 v7, 2, v5
	v_lshlrev_b32_e32 v4, 5, v4
	v_ashrrev_i16_sdwa v0, v3, sext(v0) dst_sel:DWORD dst_unused:UNUSED_PAD src0_sel:DWORD src1_sel:BYTE_0
	s_lshl_b32 s8, s7, 3
	v_and_b32_e32 v6, 0x7fffc0, v6
	v_and_b32_e32 v7, 4, v7
	v_and_b32_e32 v4, 32, v4
	v_bfe_i32 v0, v0, 0, 16
	s_sub_i32 s9, 64, s8
	s_lshl_b32 s7, s7, 6
	v_or3_b32 v2, v2, v6, v7
	v_add_lshl_u32 v0, v4, v0, 1
	s_min_u32 s9, s9, 8
	s_sub_i32 s16, s6, s7
	v_lshl_add_u32 v134, v2, 9, v0
	s_sext_i32_i8 s6, s16
	v_cvt_f32_ubyte0_e32 v2, s9
	v_cvt_f32_i32_e32 v1, s6
	v_rcp_iflag_f32_e32 v3, v2
	v_lshl_add_u32 v138, v5, 9, v0
	s_ashr_i32 s18, s52, 6
	s_ashr_i32 s6, s6, 30
	v_mul_f32_e32 v0, v1, v3
	v_trunc_f32_e32 v0, v0
	v_fma_f32 v1, -v0, v2, v1
	v_cvt_i32_f32_e32 v0, v0
	s_ashr_i32 s11, s52, 8
	s_lshl_b32 s57, s18, 10
	s_or_b32 s10, s6, 1
	v_cmp_ge_f32_e64 s[6:7], |v1|, v2
	s_and_b64 s[6:7], s[6:7], exec
	s_cselect_b32 s6, s10, 0
	v_readfirstlane_b32 s7, v0
	s_add_i32 s10, s7, s6
	s_mul_i32 s6, s10, s9
	s_sub_i32 s6, s16, s6
	s_sext_i32_i8 s6, s6
	s_add_i32 s38, s8, s6
	s_ashr_i32 s39, s38, 31
	s_bfe_i64 s[8:9], s[10:11], 0x80000
	s_lshl_b64 s[6:7], s[38:39], 17
	s_lshl_b64 s[8:9], s[8:9], 17
	s_add_u32 s40, s55, s8
	s_addc_u32 s41, s56, s9
	s_add_i32 s39, s57, 0
	s_add_i32 m0, s39, 0x10000
	v_add_u32_e32 v136, 0x1000, v134
	global_load_lds_dwordx4 v134, s[40:41]
	s_add_i32 m0, s39, 0x12000
	s_add_u32 s42, s53, s6
	global_load_lds_dwordx4 v128, s[40:41]
	s_addc_u32 s43, s54, s7
	s_mov_b32 m0, s39
	s_add_i32 s59, s39, 0x2000
	global_load_lds_dwordx4 v138, s[42:43]
	s_mov_b32 m0, s59
	v_add_u32_e32 v130, 0x1000, v128
	global_load_lds_dwordx4 v132, s[42:43]
	s_add_i32 m0, s39, 0x14000
	v_mov_b32_e32 v135, 0
	global_load_lds_dwordx4 v136, s[40:41]
	s_add_i32 m0, s39, 0x16000
	s_add_u32 s6, s42, 0x10000
	s_addc_u32 s7, s43, 0
	s_add_i32 s60, s39, 0x4000
	global_load_lds_dwordx4 v130, s[40:41]
	s_mov_b32 m0, s60
	s_add_i32 s61, s39, 0x6000
	global_load_lds_dwordx4 v138, s[6:7]
	s_mov_b32 m0, s61
	v_mov_b32_e32 v129, v135
	global_load_lds_dwordx4 v132, s[6:7]
	v_mov_b32_e32 v139, v135
	v_mov_b32_e32 v133, v135
	v_mov_b32_e32 v137, v135
	v_mov_b32_e32 v131, v135
	s_mov_b32 s62, 0
	v_lshl_add_u64 v[10:11], s[40:41], 0, v[134:135]
	v_lshl_add_u64 v[8:9], s[40:41], 0, v[128:129]
	v_lshl_add_u64 v[6:7], s[42:43], 0, v[138:139]
	v_lshl_add_u64 v[4:5], s[42:43], 0, v[132:133]
	v_lshl_add_u64 v[0:1], s[40:41], 0, v[136:137]
	s_cmp_lg_u32 s11, 1
	v_lshl_add_u64 v[2:3], s[40:41], 0, v[130:131]
	s_setprio 1
	s_cbranch_scc1 .LBB0_242
	s_barrier
	s_setprio 0

;     __device__ bool next(int i, Unit& u) const {
;         if (i >= icnt) return false;
;         const long L = (long)(i + ioff) * G + c; if (L >= nwg) return false;
; template <class Epi>
; __device__ __forceinline__ void gemm_phase(LAS unsigned char* lds, const Gemm g, const StaticOrder& S, const Epi& E) {
;     int tid = threadIdx.x; asm volatile("" : "+v"(tid));
;     const int wid = __builtin_amdgcn_readfirstlane(tid >> 6), lane = tid & 63, wr = wid >> 2, wc = wid & 3, fr = lane & 15, fq = lane >> 4;
;     const int K = g.K, nt = K / BK;
;     unsigned voffA[2], voffB0[2], voffB1[2];
; #pragma unroll
;     for (int i = 0; i < 2; ++i) { int R, C; stage_rc(tid * 16 + i * 8192, R, C);
;         const int Rw = 64 * (R >> 5) + 16 * ((R >> 2) & 3) + 4 * ((R >> 4) & 1) + (R & 3);
;         const int Rf = 64 * (R >> 5) + 8 * ((R >> 2) & 3) + 4 * ((R >> 4) & 1) + (R & 3);
;         const int Rb0 = Epi::PERM ? (Epi::F32OUT ? Rf : Rw) : R, Rb1 = Epi::PERM ? (Epi::F32OUT ? Rf + 32 : Rw + 8) : R + HALF;
;         voffA[i] = (unsigned)(R * K + C) * 2u; voffB0[i] = (unsigned)(Rb0 * K + C) * 2u; voffB1[i] = (unsigned)(Rb1 * K + C) * 2u; }
;     const size_t kstep = (size_t)(BK * 2);
;     const size_t hstep = (size_t)HALF * K * 2;
;     const size_t tstep = 2 * hstep;
;     const unsigned ldsw = (unsigned)wid * 1024u;
;     const int aoff = lds_byte(wr * 64 + fr, fq * 8), boff = lds_byte(wc * 32 + fr, fq * 8);
;     ...
;     Unit cur, nxt; int ui = 0;
;     if (!S.next(0, cur)) return;
;     f32x4 acc[2][2][4][2];
; #pragma unroll
;     for (int a = 0; a < 2; ++a)
; #pragma unroll
;         for (int b = 0; b < 2; ++b)
; #pragma unroll
;             for (int m = 0; m < 4; ++m)
; #pragma unroll
;                 for (int n = 0; n < 2; ++n) acc[a][b][m][n] = (f32x4){0.f, 0.f, 0.f, 0.f};
;     bf16x8 At[4][2], B0[2][2], B1[2][2];
;     const char* cA = (const char*)g.A + (size_t)cur.pm * tstep; const char* cB = (const char*)g.Bt + (size_t)cur.pn * tstep;
;     PG8_STAGE(PG8_SB(0, 0), cB, voffB0); PG8_STAGE(PG8_SA(0, 0), cA, voffA); PG8_STAGE(PG8_SB(0, 1), cB, voffB1); PG8_STAGE(PG8_SA(0, 1), cA + hstep, voffA);
;     if (wr == 1) PG8_BAR;
;     PG8_WAIT_V(4); PG8_BAR;
;     PG8_STAGE(PG8_SB(1, 0), cB + kstep, voffB0); PG8_STAGE(PG8_SA(1, 0), cA + kstep, voffA); PG8_STAGE(PG8_SB(1, 1), cB + kstep, voffB1);
;     PG8_WAIT_V(6); PG8_BAR;
.LBB0_600:
	s_load_dwordx4 s[16:19], s[8:9], 0x0
	s_and_b64 vcc, exec, s[4:5]
	s_cbranch_vccnz .LBB0_633
	v_ashrrev_i32_e32 v1, 31, v12
	v_lshrrev_b32_e32 v1, 26, v1
	v_add_u32_e32 v1, v12, v1
	v_ashrrev_i32_e32 v13, 6, v1
	v_bfe_i32 v1, v12, 27, 1
	v_lshlrev_b32_e32 v0, 4, v12
	v_lshrrev_b32_e32 v1, 22, v1
	v_add_u32_e32 v1, v0, v1
	v_and_b32_e32 v1, 0xfffffc00, v1
	v_sub_u32_e32 v1, v0, v1
	v_lshrrev_b32_e32 v2, 4, v1
	v_bitop3_b32 v1, v2, v1, 32 bitop3:0x6c
	v_ashrrev_i32_e32 v3, 31, v1
	v_lshrrev_b32_e32 v3, 26, v3
	v_add_u32_e32 v3, v1, v3
	v_lshlrev_b32_e32 v2, 3, v13
	v_ashrrev_i32_e32 v14, 6, v3
	v_and_b32_e32 v3, 0xc0, v3
	v_and_b32_e32 v2, -16, v2
	v_sub_u32_e32 v1, v1, v3
	v_mov_b32_e32 v3, 1
	v_add_u32_e32 v2, v14, v2
	v_ashrrev_i16_sdwa v1, v3, sext(v1) dst_sel:DWORD dst_unused:UNUSED_PAD src0_sel:DWORD src1_sel:BYTE_0
	v_lshlrev_b32_e32 v4, 5, v13
	v_bfe_i32 v15, v1, 0, 16
	v_lshlrev_b32_e32 v1, 1, v2
	v_lshlrev_b32_e32 v5, 2, v2
	v_lshrrev_b32_e32 v6, 2, v2
	v_and_b32_e32 v7, 3, v14
	v_and_b32_e32 v4, 32, v4
	v_and_b32_e32 v1, 0xfffc0, v1
	v_and_b32_e32 v6, 4, v6
	v_and_or_b32 v5, v5, 48, v7
	v_or3_b32 v1, v5, v1, v6
	v_add_lshl_u32 v4, v4, v15, 1
	v_add_u32_e32 v0, 0x2000, v0
	v_lshl_add_u32 v130, v1, 12, v4
	v_ashrrev_i32_e32 v1, 31, v0
	v_lshrrev_b32_e32 v1, 22, v1
	v_add_u32_e32 v1, v0, v1
	s_waitcnt vmcnt(5)
	v_ashrrev_i32_e32 v16, 10, v1
	v_mul_i32_i24_e32 v1, 0x400, v16
	v_sub_u32_e32 v0, v0, v1
	v_lshrrev_b32_e32 v1, 4, v0
	v_bitop3_b32 v0, v1, v0, 32 bitop3:0x6c
	s_waitcnt lgkmcnt(0)
	s_add_u32 s61, s6, 0xec00000
	v_lshl_add_u32 v128, v2, 12, v4
	v_ashrrev_i32_e32 v2, 31, v0
	s_addc_u32 s62, s7, 0
	v_lshrrev_b32_e32 v2, 26, v2
	s_add_u32 s63, s6, 0x5b80000
	v_add_u32_e32 v2, v0, v2
	s_addc_u32 s64, s7, 0
	s_ashr_i32 s8, s60, 6
	v_lshlrev_b32_e32 v1, 3, v16
	v_ashrrev_i32_e32 v17, 6, v2
	v_and_b32_e32 v2, 0xc0, v2
	s_ashr_i32 s53, s52, 31
	s_ashr_i32 s51, s50, 31
	v_and_b32_e32 v1, -16, v1
	v_sub_u32_e32 v0, v0, v2
	s_ashr_i32 s9, s60, 8
	s_lshl_b32 s65, s8, 10
	s_lshl_b64 s[10:11], s[52:53], 20
	s_lshl_b64 s[12:13], s[50:51], 20
	v_add_u32_e32 v1, v17, v1
	v_ashrrev_i16_sdwa v0, v3, sext(v0) dst_sel:DWORD dst_unused:UNUSED_PAD src0_sel:DWORD src1_sel:BYTE_0
	s_add_u32 s56, s63, s12
	v_lshlrev_b32_e32 v4, 5, v16
	v_bfe_i32 v18, v0, 0, 16
	v_lshlrev_b32_e32 v0, 1, v1
	v_lshlrev_b32_e32 v2, 2, v1
	v_lshrrev_b32_e32 v3, 2, v1
	v_and_b32_e32 v5, 3, v17
	s_addc_u32 s57, s64, s13
	s_add_i32 s53, s65, 0
	v_and_b32_e32 v4, 32, v4
	v_and_b32_e32 v0, 0xfffc0, v0
	v_and_b32_e32 v3, 4, v3
	v_and_or_b32 v2, v2, 48, v5
	s_add_i32 m0, s53, 0x10000
	v_or3_b32 v0, v2, v0, v3
	v_add_lshl_u32 v2, v4, v18, 1
	global_load_lds_dwordx4 v130, s[56:57]
	s_add_i32 m0, s53, 0x12000
	v_lshl_add_u32 v136, v0, 12, v2
	s_add_u32 s54, s61, s10
	global_load_lds_dwordx4 v136, s[56:57]
	s_addc_u32 s55, s62, s11
	s_mov_b32 m0, s53
	s_add_i32 s66, s53, 0x2000
	v_lshl_add_u32 v134, v1, 12, v2
	global_load_lds_dwordx4 v128, s[54:55]
	s_mov_b32 m0, s66
	v_add_u32_e32 v132, 0x8000, v130
	global_load_lds_dwordx4 v134, s[54:55]
	s_add_i32 m0, s53, 0x14000
	v_add_u32_e32 v138, 0x8000, v136
	global_load_lds_dwordx4 v132, s[56:57]
	s_add_i32 m0, s53, 0x16000
	s_add_u32 s10, s54, 0x80000
	s_addc_u32 s11, s55, 0
	s_add_i32 s67, s53, 0x4000
	global_load_lds_dwordx4 v138, s[56:57]
	s_mov_b32 m0, s67
	s_add_i32 s68, s53, 0x6000
	global_load_lds_dwordx4 v128, s[10:11]
	s_mov_b32 m0, s68
	v_mov_b32_e32 v131, 0
	global_load_lds_dwordx4 v134, s[10:11]
	v_mov_b32_e32 v137, v131
	v_mov_b32_e32 v129, v131
	v_mov_b32_e32 v135, v131
	v_mov_b32_e32 v133, v131
	v_mov_b32_e32 v139, v131
	s_mov_b32 s69, 0x8000
	s_movk_i32 s70, 0x2000
	s_mov_b32 s71, 0
	v_lshl_add_u64 v[10:11], s[56:57], 0, v[130:131]
	v_lshl_add_u64 v[8:9], s[56:57], 0, v[136:137]
	v_lshl_add_u64 v[6:7], s[54:55], 0, v[128:129]
	v_lshl_add_u64 v[4:5], s[54:55], 0, v[134:135]
	v_lshl_add_u64 v[0:1], s[56:57], 0, v[132:133]
	s_cmp_lg_u32 s9, 1
	v_lshl_add_u64 v[2:3], s[56:57], 0, v[138:139]
	s_setprio 1
	s_cbranch_scc1 .LBB0_603
	s_barrier
	s_setprio 0

;     __device__ bool next(int i, Unit& u) const {
;         if (i >= icnt) return false;
;         const long L = (long)(i + ioff) * G + c; if (L >= nwg) return false;
; template <class Epi>
; __device__ __forceinline__ void gemm_phase(LAS unsigned char* lds, const Gemm g, const StaticOrder& S, const Epi& E) {
;     int tid = threadIdx.x; asm volatile("" : "+v"(tid));
;     const int wid = __builtin_amdgcn_readfirstlane(tid >> 6), lane = tid & 63, wr = wid >> 2, wc = wid & 3, fr = lane & 15, fq = lane >> 4;
;     const int K = g.K, nt = K / BK;
;     unsigned voffA[2], voffB0[2], voffB1[2];
; #pragma unroll
;     for (int i = 0; i < 2; ++i) { int R, C; stage_rc(tid * 16 + i * 8192, R, C);
;         const int Rw = 64 * (R >> 5) + 16 * ((R >> 2) & 3) + 4 * ((R >> 4) & 1) + (R & 3);
;         const int Rf = 64 * (R >> 5) + 8 * ((R >> 2) & 3) + 4 * ((R >> 4) & 1) + (R & 3);
;         const int Rb0 = Epi::PERM ? (Epi::F32OUT ? Rf : Rw) : R, Rb1 = Epi::PERM ? (Epi::F32OUT ? Rf + 32 : Rw + 8) : R + HALF;
;         voffA[i] = (unsigned)(R * K + C) * 2u; voffB0[i] = (unsigned)(Rb0 * K + C) * 2u; voffB1[i] = (unsigned)(Rb1 * K + C) * 2u; }
;     const size_t kstep = (size_t)(BK * 2);
;     const size_t hstep = (size_t)HALF * K * 2;
;     const size_t tstep = 2 * hstep;
;     const unsigned ldsw = (unsigned)wid * 1024u;
;     const int aoff = lds_byte(wr * 64 + fr, fq * 8), boff = lds_byte(wc * 32 + fr, fq * 8);
;     ...
;     Unit cur, nxt; int ui = 0;
;     if (!S.next(0, cur)) return;
;     f32x4 acc[2][2][4][2];
; #pragma unroll
;     for (int a = 0; a < 2; ++a)
; #pragma unroll
;         for (int b = 0; b < 2; ++b)
; #pragma unroll
;             for (int m = 0; m < 4; ++m)
; #pragma unroll
;                 for (int n = 0; n < 2; ++n) acc[a][b][m][n] = (f32x4){0.f, 0.f, 0.f, 0.f};
;     bf16x8 At[4][2], B0[2][2], B1[2][2];
;     const char* cA = (const char*)g.A + (size_t)cur.pm * tstep; const char* cB = (const char*)g.Bt + (size_t)cur.pn * tstep;
;     PG8_STAGE(PG8_SB(0, 0), cB, voffB0); PG8_STAGE(PG8_SA(0, 0), cA, voffA); PG8_STAGE(PG8_SB(0, 1), cB, voffB1); PG8_STAGE(PG8_SA(0, 1), cA + hstep, voffA);
;     if (wr == 1) PG8_BAR;
;     PG8_WAIT_V(4); PG8_BAR;
;     PG8_STAGE(PG8_SB(1, 0), cB + kstep, voffB0); PG8_STAGE(PG8_SA(1, 0), cA + kstep, voffA); PG8_STAGE(PG8_SB(1, 1), cB + kstep, voffB1);
;     PG8_WAIT_V(6); PG8_BAR;
.LBB0_635:
	s_and_b64 vcc, exec, s[4:5]
	s_cbranch_vccnz .LBB0_665
	v_bfe_i32 v2, v12, 27, 1
	v_lshlrev_b32_e32 v0, 4, v12
	v_lshrrev_b32_e32 v2, 22, v2
	v_add_u32_e32 v2, v0, v2
	v_and_b32_e32 v2, 0xfffffc00, v2
	v_sub_u32_e32 v2, v0, v2
	v_ashrrev_i32_e32 v1, 31, v12
	v_lshrrev_b32_e32 v3, 4, v2
	v_lshrrev_b32_e32 v1, 26, v1
	v_bitop3_b32 v2, v3, v2, 32 bitop3:0x6c
	v_add_u32_e32 v1, v12, v1
	v_ashrrev_i32_e32 v4, 31, v2
	v_ashrrev_i32_e32 v1, 6, v1
	v_lshrrev_b32_e32 v4, 26, v4
	v_lshlrev_b32_e32 v3, 3, v1
	v_add_u32_e32 v4, v2, v4
	v_and_b32_e32 v3, -16, v3
	v_ashrrev_i32_e32 v5, 6, v4
	v_and_b32_e32 v4, 0xc0, v4
	v_add_u32_e32 v3, v5, v3
	v_sub_u32_e32 v2, v2, v4
	v_mov_b32_e32 v4, 1
	v_lshlrev_b32_e32 v1, 5, v1
	v_ashrrev_i16_sdwa v2, v4, sext(v2) dst_sel:DWORD dst_unused:UNUSED_PAD src0_sel:DWORD src1_sel:BYTE_0
	v_lshlrev_b32_e32 v6, 1, v3
	v_lshlrev_b32_e32 v7, 2, v3
	v_lshrrev_b32_e32 v8, 2, v3
	v_and_b32_e32 v5, 3, v5
	v_and_b32_e32 v1, 32, v1
	v_bfe_i32 v2, v2, 0, 16
	v_and_b32_e32 v6, 0x7fffc0, v6
	v_and_b32_e32 v8, 4, v8
	v_and_or_b32 v5, v7, 48, v5
	v_or3_b32 v5, v5, v6, v8
	v_add_lshl_u32 v1, v1, v2, 1
	v_add_u32_e32 v0, 0x2000, v0
	v_lshl_add_u32 v128, v3, 9, v1
	v_lshl_add_u32 v130, v5, 9, v1
	v_ashrrev_i32_e32 v1, 31, v0
	v_lshrrev_b32_e32 v1, 22, v1
	s_load_dwordx2 s[6:7], s[6:7], 0xf0
	v_add_u32_e32 v1, v0, v1
	v_ashrrev_i32_e32 v1, 10, v1
	v_mul_i32_i24_e32 v2, 0x400, v1
	v_sub_u32_e32 v0, v0, v2
	v_lshrrev_b32_e32 v2, 4, v0
	s_waitcnt lgkmcnt(0)
	s_add_u32 s61, s6, 0xe400000
	v_bitop3_b32 v0, v2, v0, 32 bitop3:0x6c
	s_addc_u32 s62, s7, 0
	v_ashrrev_i32_e32 v3, 31, v0
	s_add_u32 s63, s6, 0x4800000
	v_lshrrev_b32_e32 v3, 26, v3
	s_addc_u32 s64, s7, 0
	s_ashr_i32 s8, s60, 6
	v_lshlrev_b32_e32 v2, 3, v1
	v_add_u32_e32 v3, v0, v3
	s_ashr_i32 s47, s46, 31
	s_ashr_i32 s45, s44, 31
	v_and_b32_e32 v2, -16, v2
	v_ashrrev_i32_e32 v5, 6, v3
	v_and_b32_e32 v3, 0xc0, v3
	s_ashr_i32 s9, s60, 8
	s_lshl_b32 s65, s8, 10
	s_lshl_b64 s[10:11], s[46:47], 17
	s_lshl_b64 s[12:13], s[44:45], 17
	v_add_u32_e32 v2, v5, v2
	v_sub_u32_e32 v0, v0, v3
	s_add_u32 s48, s63, s12
	v_lshlrev_b32_e32 v1, 5, v1
	v_ashrrev_i16_sdwa v0, v4, sext(v0) dst_sel:DWORD dst_unused:UNUSED_PAD src0_sel:DWORD src1_sel:BYTE_0
	v_lshlrev_b32_e32 v3, 1, v2
	v_lshlrev_b32_e32 v4, 2, v2
	v_lshrrev_b32_e32 v6, 2, v2
	v_and_b32_e32 v5, 3, v5
	s_addc_u32 s49, s64, s13
	s_add_i32 s47, s65, 0
	v_and_b32_e32 v1, 32, v1
	v_bfe_i32 v0, v0, 0, 16
	v_and_b32_e32 v3, 0x7fffc0, v3
	v_and_b32_e32 v6, 4, v6
	v_and_or_b32 v4, v4, 48, v5
	s_add_i32 m0, s47, 0x10000
	v_or3_b32 v3, v4, v3, v6
	v_add_lshl_u32 v0, v1, v0, 1
	global_load_lds_dwordx4 v130, s[48:49]
	s_add_i32 m0, s47, 0x12000
	v_lshl_add_u32 v136, v3, 9, v0
	s_add_u32 s50, s61, s10
	global_load_lds_dwordx4 v136, s[48:49]
	s_addc_u32 s51, s62, s11
	s_mov_b32 m0, s47
	s_add_i32 s66, s47, 0x2000
	v_lshl_add_u32 v134, v2, 9, v0
	global_load_lds_dwordx4 v128, s[50:51]
	s_mov_b32 m0, s66
	v_add_u32_e32 v132, 0x1000, v130
	global_load_lds_dwordx4 v134, s[50:51]
	s_add_i32 m0, s47, 0x14000
	v_add_u32_e32 v138, 0x1000, v136
	global_load_lds_dwordx4 v132, s[48:49]
	s_add_i32 m0, s47, 0x16000
	s_add_u32 s10, s50, 0x10000
	s_addc_u32 s11, s51, 0
	s_add_i32 s67, s47, 0x4000
	global_load_lds_dwordx4 v138, s[48:49]
	s_mov_b32 m0, s67
	s_add_i32 s68, s47, 0x6000
	global_load_lds_dwordx4 v128, s[10:11]
	s_mov_b32 m0, s68
	v_mov_b32_e32 v131, 0
	global_load_lds_dwordx4 v134, s[10:11]
	v_mov_b32_e32 v137, v131
	v_mov_b32_e32 v129, v131
	v_mov_b32_e32 v135, v131
	v_mov_b32_e32 v133, v131
	v_mov_b32_e32 v139, v131
	s_mov_b32 s69, 0
	v_lshl_add_u64 v[10:11], s[48:49], 0, v[130:131]
	v_lshl_add_u64 v[8:9], s[48:49], 0, v[136:137]
	v_lshl_add_u64 v[6:7], s[50:51], 0, v[128:129]
	v_lshl_add_u64 v[4:5], s[50:51], 0, v[134:135]
	v_lshl_add_u64 v[0:1], s[48:49], 0, v[132:133]
	s_cmp_lg_u32 s9, 1
	v_lshl_add_u64 v[2:3], s[48:49], 0, v[138:139]
	s_setprio 1
	s_cbranch_scc1 .LBB0_638
	s_barrier
	s_setprio 0

;     __device__ bool next(int i, Unit& u) const {
;         if (i >= icnt) return false;
;         const long L = (long)(i + ioff) * G + c; if (L >= nwg) return false;
; template <class Epi>
; __device__ __forceinline__ void gemm_phase(LAS unsigned char* lds, const Gemm g, const StaticOrder& S, const Epi& E) {
;     int tid = threadIdx.x; asm volatile("" : "+v"(tid));
;     const int wid = __builtin_amdgcn_readfirstlane(tid >> 6), lane = tid & 63, wr = wid >> 2, wc = wid & 3, fr = lane & 15, fq = lane >> 4;
;     const int K = g.K, nt = K / BK;
;     unsigned voffA[2], voffB0[2], voffB1[2];
; #pragma unroll
;     for (int i = 0; i < 2; ++i) { int R, C; stage_rc(tid * 16 + i * 8192, R, C);
;         const int Rw = 64 * (R >> 5) + 16 * ((R >> 2) & 3) + 4 * ((R >> 4) & 1) + (R & 3);
;         const int Rf = 64 * (R >> 5) + 8 * ((R >> 2) & 3) + 4 * ((R >> 4) & 1) + (R & 3);
;         const int Rb0 = Epi::PERM ? (Epi::F32OUT ? Rf : Rw) : R, Rb1 = Epi::PERM ? (Epi::F32OUT ? Rf + 32 : Rw + 8) : R + HALF;
;         voffA[i] = (unsigned)(R * K + C) * 2u; voffB0[i] = (unsigned)(Rb0 * K + C) * 2u; voffB1[i] = (unsigned)(Rb1 * K + C) * 2u; }
;     const size_t kstep = (size_t)(BK * 2);
;     const size_t hstep = (size_t)HALF * K * 2;
;     const size_t tstep = 2 * hstep;
;     const unsigned ldsw = (unsigned)wid * 1024u;
;     const int aoff = lds_byte(wr * 64 + fr, fq * 8), boff = lds_byte(wc * 32 + fr, fq * 8);
;     ...
;     Unit cur, nxt; int ui = 0;
;     if (!S.next(0, cur)) return;
;     f32x4 acc[2][2][4][2];
; #pragma unroll
;     for (int a = 0; a < 2; ++a)
; #pragma unroll
;         for (int b = 0; b < 2; ++b)
; #pragma unroll
;             for (int m = 0; m < 4; ++m)
; #pragma unroll
;                 for (int n = 0; n < 2; ++n) acc[a][b][m][n] = (f32x4){0.f, 0.f, 0.f, 0.f};
;     bf16x8 At[4][2], B0[2][2], B1[2][2];
;     const char* cA = (const char*)g.A + (size_t)cur.pm * tstep; const char* cB = (const char*)g.Bt + (size_t)cur.pn * tstep;
;     PG8_STAGE(PG8_SB(0, 0), cB, voffB0); PG8_STAGE(PG8_SA(0, 0), cA, voffA); PG8_STAGE(PG8_SB(0, 1), cB, voffB1); PG8_STAGE(PG8_SA(0, 1), cA + hstep, voffA);
;     if (wr == 1) PG8_BAR;
;     PG8_WAIT_V(4); PG8_BAR;
;     PG8_STAGE(PG8_SB(1, 0), cB + kstep, voffB0); PG8_STAGE(PG8_SA(1, 0), cA + kstep, voffA); PG8_STAGE(PG8_SB(1, 1), cB + kstep, voffB1);
;     PG8_WAIT_V(6); PG8_BAR;
.LBB0_722:
	v_ashrrev_i32_e32 v1, 31, v12
	v_lshrrev_b32_e32 v1, 26, v1
	v_add_u32_e32 v1, v12, v1
	v_ashrrev_i32_e32 v13, 6, v1
	v_bfe_i32 v1, v12, 27, 1
	v_lshlrev_b32_e32 v0, 4, v12
	v_lshrrev_b32_e32 v1, 22, v1
	v_add_u32_e32 v1, v0, v1
	v_and_b32_e32 v1, 0xfffffc00, v1
	v_sub_u32_e32 v1, v0, v1
	v_lshrrev_b32_e32 v2, 4, v1
	v_bitop3_b32 v1, v2, v1, 32 bitop3:0x6c
	v_ashrrev_i32_e32 v3, 31, v1
	v_lshrrev_b32_e32 v3, 26, v3
	v_add_u32_e32 v3, v1, v3
	v_lshlrev_b32_e32 v2, 3, v13
	v_ashrrev_i32_e32 v14, 6, v3
	v_and_b32_e32 v3, 0xc0, v3
	v_and_b32_e32 v2, -16, v2
	v_sub_u32_e32 v1, v1, v3
	v_mov_b32_e32 v3, 1
	s_ashr_i32 s6, s11, 3
	v_add_u32_e32 v2, v14, v2
	v_ashrrev_i16_sdwa v1, v3, sext(v1) dst_sel:DWORD dst_unused:UNUSED_PAD src0_sel:DWORD src1_sel:BYTE_0
	s_waitcnt lgkmcnt(0)
	s_add_u32 s54, s8, 0x6400000
	v_lshlrev_b32_e32 v4, 5, v13
	v_bfe_i32 v15, v1, 0, 16
	v_lshlrev_b32_e32 v1, 1, v2
	v_lshlrev_b32_e32 v5, 2, v2
	v_lshrrev_b32_e32 v6, 2, v2
	v_and_b32_e32 v7, 3, v14
	s_addc_u32 s55, s9, 0
	v_and_b32_e32 v4, 32, v4
	v_and_b32_e32 v1, 0xfffc0, v1
	v_and_b32_e32 v6, 4, v6
	v_and_or_b32 v5, v5, 48, v7
	s_add_i32 s6, s10, s6
	v_or3_b32 v1, v5, v1, v6
	v_add_lshl_u32 v4, v4, v15, 1
	v_add_u32_e32 v0, 0x2000, v0
	s_ashr_i32 s10, s6, 31
	v_lshl_add_u32 v130, v1, 12, v4
	v_ashrrev_i32_e32 v1, 31, v0
	s_lshr_b32 s10, s10, 24
	v_lshrrev_b32_e32 v1, 22, v1
	s_add_i32 s10, s6, s10
	v_add_u32_e32 v1, v0, v1
	s_ashr_i32 s11, s10, 8
	s_and_b32 s10, s10, 0xffffff00
	v_ashrrev_i32_e32 v16, 10, v1
	s_sub_i32 s10, s6, s10
	v_mul_i32_i24_e32 v1, 0x400, v16
	s_sext_i32_i16 s6, s10
	v_sub_u32_e32 v0, v0, v1
	s_bfe_u32 s6, s6, 0x3001c
	v_lshrrev_b32_e32 v1, 4, v0
	s_add_i32 s16, s10, s6
	v_bitop3_b32 v0, v1, v0, 32 bitop3:0x6c
	s_sext_i32_i16 s6, s16
	s_and_b32 s16, s16, 0xfff8
	v_lshl_add_u32 v128, v2, 12, v4
	v_ashrrev_i32_e32 v2, 31, v0
	s_sub_i32 s10, s10, s16
	v_lshrrev_b32_e32 v2, 26, v2
	s_lshl_b32 s11, s11, 3
	s_sext_i32_i16 s10, s10
	s_ashr_i32 s7, s52, 6
	v_add_u32_e32 v2, v0, v2
	s_lshr_b32 s6, s6, 3
	s_add_i32 s44, s11, s10
	v_lshlrev_b32_e32 v1, 3, v16
	v_ashrrev_i32_e32 v17, 6, v2
	v_and_b32_e32 v2, 0xc0, v2
	s_ashr_i32 s45, s44, 31
	s_bfe_i64 s[16:17], s[6:7], 0x100000
	v_and_b32_e32 v1, -16, v1
	v_sub_u32_e32 v0, v0, v2
	s_ashr_i32 s18, s52, 8
	s_lshl_b32 s56, s7, 10
	s_lshl_b64 s[10:11], s[44:45], 20
	s_lshl_b64 s[16:17], s[16:17], 20
	v_add_u32_e32 v1, v17, v1
	v_ashrrev_i16_sdwa v0, v3, sext(v0) dst_sel:DWORD dst_unused:UNUSED_PAD src0_sel:DWORD src1_sel:BYTE_0
	s_add_u32 s48, s8, s16
	v_lshlrev_b32_e32 v4, 5, v16
	v_bfe_i32 v18, v0, 0, 16
	v_lshlrev_b32_e32 v0, 1, v1
	v_lshlrev_b32_e32 v2, 2, v1
	v_lshrrev_b32_e32 v3, 2, v1
	v_and_b32_e32 v5, 3, v17
	s_addc_u32 s49, s9, s17
	s_add_i32 s45, s56, 0
	v_and_b32_e32 v4, 32, v4
	v_and_b32_e32 v0, 0xfffc0, v0
	v_and_b32_e32 v3, 4, v3
	v_and_or_b32 v2, v2, 48, v5
	s_add_i32 m0, s45, 0x10000
	v_or3_b32 v0, v2, v0, v3
	v_add_lshl_u32 v2, v4, v18, 1
	global_load_lds_dwordx4 v130, s[48:49]
	s_add_i32 m0, s45, 0x12000
	v_lshl_add_u32 v136, v0, 12, v2
	s_add_u32 s46, s54, s10
	global_load_lds_dwordx4 v136, s[48:49]
	s_addc_u32 s47, s55, s11
	s_mov_b32 m0, s45
	s_add_i32 s57, s45, 0x2000
	v_lshl_add_u32 v134, v1, 12, v2
	global_load_lds_dwordx4 v128, s[46:47]
	s_mov_b32 m0, s57
	v_add_u32_e32 v132, 0x8000, v130
	global_load_lds_dwordx4 v134, s[46:47]
	s_add_i32 m0, s45, 0x14000
	v_add_u32_e32 v138, 0x8000, v136
	global_load_lds_dwordx4 v132, s[48:49]
	s_add_i32 m0, s45, 0x16000
	s_add_u32 s10, s46, 0x80000
	s_addc_u32 s11, s47, 0
	s_add_i32 s58, s45, 0x4000
	global_load_lds_dwordx4 v138, s[48:49]
	s_mov_b32 m0, s58
	s_add_i32 s59, s45, 0x6000
	global_load_lds_dwordx4 v128, s[10:11]
	s_mov_b32 m0, s59
	v_mov_b32_e32 v131, 0
	global_load_lds_dwordx4 v134, s[10:11]
	v_mov_b32_e32 v137, v131
	v_mov_b32_e32 v129, v131
	v_mov_b32_e32 v135, v131
	v_mov_b32_e32 v133, v131
	v_mov_b32_e32 v139, v131
	s_mov_b32 s60, 0
	v_lshl_add_u64 v[10:11], s[48:49], 0, v[130:131]
	v_lshl_add_u64 v[8:9], s[48:49], 0, v[136:137]
	v_lshl_add_u64 v[6:7], s[46:47], 0, v[128:129]
	v_lshl_add_u64 v[4:5], s[46:47], 0, v[134:135]
	v_lshl_add_u64 v[0:1], s[48:49], 0, v[132:133]
	s_cmp_lg_u32 s18, 1
	v_lshl_add_u64 v[2:3], s[48:49], 0, v[138:139]
	s_setprio 1
	s_cbranch_scc1 .LBB0_724
	s_barrier
	s_setprio 0

;     __device__ bool next(int i, Unit& u) const {
;         if (i >= icnt) return false;
;         const long L = (long)(i + ioff) * G + c; if (L >= nwg) return false;
; template <class Epi>
; __device__ __forceinline__ void gemm_phase(LAS unsigned char* lds, const Gemm g, const StaticOrder& S, const Epi& E) {
;     int tid = threadIdx.x; asm volatile("" : "+v"(tid));
;     const int wid = __builtin_amdgcn_readfirstlane(tid >> 6), lane = tid & 63, wr = wid >> 2, wc = wid & 3, fr = lane & 15, fq = lane >> 4;
;     const int K = g.K, nt = K / BK;
;     unsigned voffA[2], voffB0[2], voffB1[2];
; #pragma unroll
;     for (int i = 0; i < 2; ++i) { int R, C; stage_rc(tid * 16 + i * 8192, R, C);
;         const int Rw = 64 * (R >> 5) + 16 * ((R >> 2) & 3) + 4 * ((R >> 4) & 1) + (R & 3);
;         const int Rf = 64 * (R >> 5) + 8 * ((R >> 2) & 3) + 4 * ((R >> 4) & 1) + (R & 3);
;         const int Rb0 = Epi::PERM ? (Epi::F32OUT ? Rf : Rw) : R, Rb1 = Epi::PERM ? (Epi::F32OUT ? Rf + 32 : Rw + 8) : R + HALF;
;         voffA[i] = (unsigned)(R * K + C) * 2u; voffB0[i] = (unsigned)(Rb0 * K + C) * 2u; voffB1[i] = (unsigned)(Rb1 * K + C) * 2u; }
;     const size_t kstep = (size_t)(BK * 2);
;     const size_t hstep = (size_t)HALF * K * 2;
;     const size_t tstep = 2 * hstep;
;     const unsigned ldsw = (unsigned)wid * 1024u;
;     const int aoff = lds_byte(wr * 64 + fr, fq * 8), boff = lds_byte(wc * 32 + fr, fq * 8);
;     ...
;     Unit cur, nxt; int ui = 0;
;     if (!S.next(0, cur)) return;
;     f32x4 acc[2][2][4][2];
; #pragma unroll
;     for (int a = 0; a < 2; ++a)
; #pragma unroll
;         for (int b = 0; b < 2; ++b)
; #pragma unroll
;             for (int m = 0; m < 4; ++m)
; #pragma unroll
;                 for (int n = 0; n < 2; ++n) acc[a][b][m][n] = (f32x4){0.f, 0.f, 0.f, 0.f};
;     bf16x8 At[4][2], B0[2][2], B1[2][2];
;     const char* cA = (const char*)g.A + (size_t)cur.pm * tstep; const char* cB = (const char*)g.Bt + (size_t)cur.pn * tstep;
;     PG8_STAGE(PG8_SB(0, 0), cB, voffB0); PG8_STAGE(PG8_SA(0, 0), cA, voffA); PG8_STAGE(PG8_SB(0, 1), cB, voffB1); PG8_STAGE(PG8_SA(0, 1), cA + hstep, voffA);
;     if (wr == 1) PG8_BAR;
;     PG8_WAIT_V(4); PG8_BAR;
;     PG8_STAGE(PG8_SB(1, 0), cB + kstep, voffB0); PG8_STAGE(PG8_SA(1, 0), cA + kstep, voffA); PG8_STAGE(PG8_SB(1, 1), cB + kstep, voffB1);
;     PG8_WAIT_V(6); PG8_BAR;
.LBB0_795:
	v_ashrrev_i32_e32 v1, 31, v12
	v_lshrrev_b32_e32 v1, 26, v1
	v_add_u32_e32 v1, v12, v1
	v_ashrrev_i32_e32 v13, 6, v1
	v_bfe_i32 v1, v12, 27, 1
	v_lshlrev_b32_e32 v0, 4, v12
	v_lshrrev_b32_e32 v1, 22, v1
	v_add_u32_e32 v1, v0, v1
	v_and_b32_e32 v1, 0xfffffc00, v1
	v_sub_u32_e32 v1, v0, v1
	v_lshrrev_b32_e32 v2, 4, v1
	v_bitop3_b32 v2, v2, v1, 32 bitop3:0x6c
	v_ashrrev_i32_e32 v1, 31, v1
	v_lshrrev_b32_e32 v1, 26, v1
	v_add_u32_e32 v1, v2, v1
	s_ashr_i32 s6, s19, 3
	v_ashrrev_i32_e32 v14, 6, v1
	s_waitcnt lgkmcnt(0)
	s_add_u32 s58, s10, 0xec00000
	v_lshlrev_b32_e32 v3, 3, v13
	v_mul_i32_i24_e32 v4, 64, v14
	s_addc_u32 s59, s11, 0
	v_and_b32_e32 v3, -16, v3
	v_sub_u32_e32 v2, v2, v4
	v_mov_b32_e32 v4, 1
	s_add_u32 s60, s10, 0x2000000
	v_add_u32_e32 v1, v14, v3
	v_lshlrev_b32_e32 v3, 5, v13
	v_ashrrev_i16_sdwa v2, v4, sext(v2) dst_sel:DWORD dst_unused:UNUSED_PAD src0_sel:DWORD src1_sel:BYTE_0
	s_addc_u32 s61, s11, 0
	v_and_b32_e32 v3, 32, v3
	v_bfe_i32 v15, v2, 0, 16
	s_add_i32 s6, s18, s6
	v_add_lshl_u32 v3, v3, v15, 1
	v_add_u32_e32 v0, 0x2000, v0
	s_ashr_i32 s16, s6, 31
	v_lshlrev_b32_e32 v2, 1, v1
	v_lshlrev_b32_e32 v5, 2, v1
	v_lshrrev_b32_e32 v6, 2, v1
	v_lshl_add_u32 v128, v1, 14, v3
	v_ashrrev_i32_e32 v1, 31, v0
	s_lshr_b32 s16, s16, 26
	v_lshrrev_b32_e32 v1, 22, v1
	s_add_i32 s16, s6, s16
	v_add_u32_e32 v1, v0, v1
	s_ashr_i32 s17, s16, 6
	s_andn2_b32 s16, s16, 63
	v_ashrrev_i32_e32 v16, 10, v1
	s_sub_i32 s16, s6, s16
	v_mul_i32_i24_e32 v1, 0x400, v16
	s_bfe_i32 s6, s16, 0x80000
	v_and_b32_e32 v7, 3, v14
	v_sub_u32_e32 v0, v0, v1
	s_bfe_u32 s6, s6, 0x3000c
	v_and_b32_e32 v2, 0x3ffc0, v2
	v_and_b32_e32 v6, 4, v6
	v_and_or_b32 v5, v5, 48, v7
	v_lshrrev_b32_e32 v1, 4, v0
	s_add_i32 s18, s16, s6
	v_or3_b32 v2, v5, v2, v6
	v_bitop3_b32 v0, v1, v0, 32 bitop3:0x6c
	s_bfe_i32 s6, s18, 0x80000
	s_and_b32 s18, s18, 0xf8
	v_lshl_add_u32 v130, v2, 14, v3
	v_ashrrev_i32_e32 v2, 31, v0
	s_sub_i32 s16, s16, s18
	v_lshrrev_b32_e32 v2, 26, v2
	s_lshl_b32 s17, s17, 3
	s_sext_i32_i16 s6, s6
	s_sext_i32_i8 s16, s16
	s_ashr_i32 s7, s56, 6
	v_add_u32_e32 v2, v0, v2
	s_lshr_b32 s6, s6, 3
	s_add_i32 s48, s17, s16
	v_lshlrev_b32_e32 v1, 3, v16
	v_ashrrev_i32_e32 v17, 6, v2
	v_and_b32_e32 v2, 0xc0, v2
	s_ashr_i32 s49, s48, 31
	s_bfe_i64 s[18:19], s[6:7], 0x100000
	v_and_b32_e32 v1, -16, v1
	v_sub_u32_e32 v0, v0, v2
	s_ashr_i32 s36, s56, 8
	s_lshl_b32 s62, s7, 10
	s_lshl_b64 s[16:17], s[48:49], 22
	s_lshl_b64 s[18:19], s[18:19], 22
	v_add_u32_e32 v1, v17, v1
	v_ashrrev_i16_sdwa v0, v4, sext(v0) dst_sel:DWORD dst_unused:UNUSED_PAD src0_sel:DWORD src1_sel:BYTE_0
	s_add_u32 s52, s60, s18
	v_lshlrev_b32_e32 v3, 5, v16
	v_bfe_i32 v18, v0, 0, 16
	v_lshlrev_b32_e32 v0, 1, v1
	v_lshlrev_b32_e32 v2, 2, v1
	v_lshrrev_b32_e32 v4, 2, v1
	v_and_b32_e32 v5, 3, v17
	s_addc_u32 s53, s61, s19
	s_add_i32 s49, s62, 0
	v_and_b32_e32 v3, 32, v3
	v_and_b32_e32 v0, 0x3ffc0, v0
	v_and_b32_e32 v4, 4, v4
	v_and_or_b32 v2, v2, 48, v5
	s_add_i32 m0, s49, 0x10000
	v_or3_b32 v0, v2, v0, v4
	v_add_lshl_u32 v2, v3, v18, 1
	global_load_lds_dwordx4 v130, s[52:53]
	s_add_i32 m0, s49, 0x12000
	v_lshl_add_u32 v136, v0, 14, v2
	s_add_u32 s50, s58, s16
	global_load_lds_dwordx4 v136, s[52:53]
	s_addc_u32 s51, s59, s17
	s_mov_b32 m0, s49
	s_add_i32 s63, s49, 0x2000
	v_lshl_add_u32 v134, v1, 14, v2
	global_load_lds_dwordx4 v128, s[50:51]
	s_mov_b32 m0, s63
	v_add_u32_e32 v132, 0x20000, v130
	global_load_lds_dwordx4 v134, s[50:51]
	s_add_i32 m0, s49, 0x14000
	v_add_u32_e32 v138, 0x20000, v136
	global_load_lds_dwordx4 v132, s[52:53]
	s_add_i32 m0, s49, 0x16000
	s_add_u32 s16, s50, 0x200000
	s_addc_u32 s17, s51, 0
	s_add_i32 s64, s49, 0x4000
	global_load_lds_dwordx4 v138, s[52:53]
	s_mov_b32 m0, s64
	s_add_i32 s65, s49, 0x6000
	global_load_lds_dwordx4 v128, s[16:17]
	s_mov_b32 m0, s65
	v_mov_b32_e32 v131, 0
	global_load_lds_dwordx4 v134, s[16:17]
	v_mov_b32_e32 v137, v131
	v_mov_b32_e32 v129, v131
	v_mov_b32_e32 v135, v131
	v_mov_b32_e32 v133, v131
	v_mov_b32_e32 v139, v131
	s_mov_b32 s66, 0
	v_lshl_add_u64 v[10:11], s[52:53], 0, v[130:131]
	v_lshl_add_u64 v[8:9], s[52:53], 0, v[136:137]
	v_lshl_add_u64 v[6:7], s[50:51], 0, v[128:129]
	v_lshl_add_u64 v[4:5], s[50:51], 0, v[134:135]
	v_lshl_add_u64 v[0:1], s[52:53], 0, v[132:133]
	s_cmp_lg_u32 s36, 1
	v_lshl_add_u64 v[2:3], s[52:53], 0, v[138:139]
	s_setprio 1
	s_cbranch_scc1 .LBB0_797
	s_barrier
	s_setprio 0

;     __device__ bool next(int i, Unit& u) const {
;         if (i >= icnt) return false;
;         const long L = (long)(i + ioff) * G + c; if (L >= nwg) return false;
; template <class Epi>
; __device__ __forceinline__ void gemm_phase(LAS unsigned char* lds, const Gemm g, const StaticOrder& S, const Epi& E) {
;     int tid = threadIdx.x; asm volatile("" : "+v"(tid));
;     const int wid = __builtin_amdgcn_readfirstlane(tid >> 6), lane = tid & 63, wr = wid >> 2, wc = wid & 3, fr = lane & 15, fq = lane >> 4;
;     const int K = g.K, nt = K / BK;
;     unsigned voffA[2], voffB0[2], voffB1[2];
; #pragma unroll
;     for (int i = 0; i < 2; ++i) { int R, C; stage_rc(tid * 16 + i * 8192, R, C);
;         const int Rw = 64 * (R >> 5) + 16 * ((R >> 2) & 3) + 4 * ((R >> 4) & 1) + (R & 3);
;         const int Rf = 64 * (R >> 5) + 8 * ((R >> 2) & 3) + 4 * ((R >> 4) & 1) + (R & 3);
;         const int Rb0 = Epi::PERM ? (Epi::F32OUT ? Rf : Rw) : R, Rb1 = Epi::PERM ? (Epi::F32OUT ? Rf + 32 : Rw + 8) : R + HALF;
;         voffA[i] = (unsigned)(R * K + C) * 2u; voffB0[i] = (unsigned)(Rb0 * K + C) * 2u; voffB1[i] = (unsigned)(Rb1 * K + C) * 2u; }
;     const size_t kstep = (size_t)(BK * 2);
;     const size_t hstep = (size_t)HALF * K * 2;
;     const size_t tstep = 2 * hstep;
;     const unsigned ldsw = (unsigned)wid * 1024u;
;     const int aoff = lds_byte(wr * 64 + fr, fq * 8), boff = lds_byte(wc * 32 + fr, fq * 8);
;     ...
;     Unit cur, nxt; int ui = 0;
;     if (!S.next(0, cur)) return;
;     f32x4 acc[2][2][4][2];
; #pragma unroll
;     for (int a = 0; a < 2; ++a)
; #pragma unroll
;         for (int b = 0; b < 2; ++b)
; #pragma unroll
;             for (int m = 0; m < 4; ++m)
; #pragma unroll
;                 for (int n = 0; n < 2; ++n) acc[a][b][m][n] = (f32x4){0.f, 0.f, 0.f, 0.f};
;     bf16x8 At[4][2], B0[2][2], B1[2][2];
;     const char* cA = (const char*)g.A + (size_t)cur.pm * tstep; const char* cB = (const char*)g.Bt + (size_t)cur.pn * tstep;
;     PG8_STAGE(PG8_SB(0, 0), cB, voffB0); PG8_STAGE(PG8_SA(0, 0), cA, voffA); PG8_STAGE(PG8_SB(0, 1), cB, voffB1); PG8_STAGE(PG8_SA(0, 1), cA + hstep, voffA);
;     if (wr == 1) PG8_BAR;
;     PG8_WAIT_V(4); PG8_BAR;
;     PG8_STAGE(PG8_SB(1, 0), cB + kstep, voffB0); PG8_STAGE(PG8_SA(1, 0), cA + kstep, voffA); PG8_STAGE(PG8_SB(1, 1), cB + kstep, voffB1);
;     PG8_WAIT_V(6); PG8_BAR;
.LBB0_869:
	s_load_dwordx4 s[16:19], s[6:7], 0xe8
	s_and_b64 vcc, exec, s[4:5]
	s_cbranch_vccnz .LBB0_902
	v_ashrrev_i32_e32 v1, 31, v12
	v_lshrrev_b32_e32 v1, 26, v1
	v_add_u32_e32 v1, v12, v1
	v_ashrrev_i32_e32 v13, 6, v1
	v_bfe_i32 v1, v12, 27, 1
	v_lshlrev_b32_e32 v0, 4, v12
	v_lshrrev_b32_e32 v1, 22, v1
	v_add_u32_e32 v1, v0, v1
	v_and_b32_e32 v1, 0xfffffc00, v1
	v_sub_u32_e32 v1, v0, v1
	v_lshrrev_b32_e32 v2, 4, v1
	v_bitop3_b32 v1, v2, v1, 32 bitop3:0x6c
	v_ashrrev_i32_e32 v3, 31, v1
	v_lshrrev_b32_e32 v3, 26, v3
	v_add_u32_e32 v3, v1, v3
	v_lshlrev_b32_e32 v2, 3, v13
	v_ashrrev_i32_e32 v14, 6, v3
	v_and_b32_e32 v3, 0xc0, v3
	v_and_b32_e32 v2, -16, v2
	v_sub_u32_e32 v1, v1, v3
	v_mov_b32_e32 v3, 1
	v_add_u32_e32 v2, v14, v2
	v_ashrrev_i16_sdwa v1, v3, sext(v1) dst_sel:DWORD dst_unused:UNUSED_PAD src0_sel:DWORD src1_sel:BYTE_0
	v_lshlrev_b32_e32 v4, 5, v13
	v_bfe_i32 v15, v1, 0, 16
	v_lshlrev_b32_e32 v1, 1, v2
	v_lshlrev_b32_e32 v5, 2, v2
	v_lshrrev_b32_e32 v6, 2, v2
	v_and_b32_e32 v7, 3, v14
	v_and_b32_e32 v4, 32, v4
	v_and_b32_e32 v1, 0xfffc0, v1
	v_and_b32_e32 v6, 4, v6
	v_and_or_b32 v5, v5, 48, v7
	v_or3_b32 v1, v5, v1, v6
	v_add_lshl_u32 v4, v4, v15, 1
	v_add_u32_e32 v0, 0x2000, v0
	v_lshl_add_u32 v146, v1, 12, v4
	v_ashrrev_i32_e32 v1, 31, v0
	v_lshrrev_b32_e32 v1, 22, v1
	v_add_u32_e32 v1, v0, v1
	v_ashrrev_i32_e32 v16, 10, v1
	v_mul_i32_i24_e32 v1, 0x400, v16
	v_sub_u32_e32 v0, v0, v1
	v_lshrrev_b32_e32 v1, 4, v0
	v_bitop3_b32 v0, v1, v0, 32 bitop3:0x6c
	v_lshl_add_u32 v144, v2, 12, v4
	v_ashrrev_i32_e32 v2, 31, v0
	v_lshrrev_b32_e32 v2, 26, v2
	s_waitcnt lgkmcnt(0)
	s_add_u32 s67, s18, 0x4000000
	v_add_u32_e32 v2, v0, v2
	s_addc_u32 s68, s19, 0
	s_ashr_i32 s6, s66, 6
	v_lshlrev_b32_e32 v1, 3, v16
	v_ashrrev_i32_e32 v17, 6, v2
	v_and_b32_e32 v2, 0xc0, v2
	s_ashr_i32 s59, s58, 31
	s_ashr_i32 s57, s56, 31
	v_and_b32_e32 v1, -16, v1
	v_sub_u32_e32 v0, v0, v2
	s_ashr_i32 s7, s66, 8
	s_lshl_b32 s69, s6, 10
	s_lshl_b64 s[8:9], s[58:59], 20
	s_lshl_b64 s[36:37], s[56:57], 20
	v_add_u32_e32 v1, v17, v1
	v_ashrrev_i16_sdwa v0, v3, sext(v0) dst_sel:DWORD dst_unused:UNUSED_PAD src0_sel:DWORD src1_sel:BYTE_0
	s_add_u32 s62, s67, s36
	v_lshlrev_b32_e32 v4, 5, v16
	v_bfe_i32 v18, v0, 0, 16
	v_lshlrev_b32_e32 v0, 1, v1
	v_lshlrev_b32_e32 v2, 2, v1
	v_lshrrev_b32_e32 v3, 2, v1
	v_and_b32_e32 v5, 3, v17
	s_addc_u32 s63, s68, s37
	s_add_i32 s59, s69, 0
	v_and_b32_e32 v4, 32, v4
	v_and_b32_e32 v0, 0xfffc0, v0
	v_and_b32_e32 v3, 4, v3
	v_and_or_b32 v2, v2, 48, v5
	s_add_i32 m0, s59, 0x10000
	v_or3_b32 v0, v2, v0, v3
	v_add_lshl_u32 v2, v4, v18, 1
	global_load_lds_dwordx4 v146, s[62:63]
	s_add_i32 m0, s59, 0x12000
	v_lshl_add_u32 v152, v0, 12, v2
	s_add_u32 s60, s16, s8
	global_load_lds_dwordx4 v152, s[62:63]
	s_addc_u32 s61, s17, s9
	s_mov_b32 m0, s59
	s_add_i32 s70, s59, 0x2000
	v_lshl_add_u32 v150, v1, 12, v2
	global_load_lds_dwordx4 v144, s[60:61]
	s_mov_b32 m0, s70
	v_add_u32_e32 v148, 0x8000, v146
	global_load_lds_dwordx4 v150, s[60:61]
	s_add_i32 m0, s59, 0x14000
	v_add_u32_e32 v154, 0x8000, v152
	global_load_lds_dwordx4 v148, s[62:63]
	s_add_i32 m0, s59, 0x16000
	s_add_u32 s8, s60, 0x80000
	s_addc_u32 s9, s61, 0
	s_add_i32 s71, s59, 0x4000
	global_load_lds_dwordx4 v154, s[62:63]
	s_mov_b32 m0, s71
	s_add_i32 s72, s59, 0x6000
	global_load_lds_dwordx4 v144, s[8:9]
	s_mov_b32 m0, s72
	v_mov_b32_e32 v147, 0
	global_load_lds_dwordx4 v150, s[8:9]
	v_mov_b32_e32 v153, v147
	v_mov_b32_e32 v145, v147
	v_mov_b32_e32 v151, v147
	v_mov_b32_e32 v149, v147
	v_mov_b32_e32 v155, v147
	s_mov_b32 s73, 0
	v_lshl_add_u64 v[10:11], s[62:63], 0, v[146:147]
	v_lshl_add_u64 v[8:9], s[62:63], 0, v[152:153]
	v_lshl_add_u64 v[6:7], s[60:61], 0, v[144:145]
	v_lshl_add_u64 v[4:5], s[60:61], 0, v[150:151]
	v_lshl_add_u64 v[0:1], s[62:63], 0, v[148:149]
	s_cmp_lg_u32 s7, 1
	v_lshl_add_u64 v[2:3], s[62:63], 0, v[154:155]
	s_setprio 1
	s_cbranch_scc1 .LBB0_872
	s_barrier
	s_setprio 0

;     __device__ bool next(int i, Unit& u) const {
;         if (i >= icnt) return false;
;         const long L = (long)(i + ioff) * G + c; if (L >= nwg) return false;
; template <class Epi>
; __device__ __forceinline__ void gemm_phase(LAS unsigned char* lds, const Gemm g, const StaticOrder& S, const Epi& E) {
;     int tid = threadIdx.x; asm volatile("" : "+v"(tid));
;     const int wid = __builtin_amdgcn_readfirstlane(tid >> 6), lane = tid & 63, wr = wid >> 2, wc = wid & 3, fr = lane & 15, fq = lane >> 4;
;     const int K = g.K, nt = K / BK;
;     unsigned voffA[2], voffB0[2], voffB1[2];
; #pragma unroll
;     for (int i = 0; i < 2; ++i) { int R, C; stage_rc(tid * 16 + i * 8192, R, C);
;         const int Rw = 64 * (R >> 5) + 16 * ((R >> 2) & 3) + 4 * ((R >> 4) & 1) + (R & 3);
;         const int Rf = 64 * (R >> 5) + 8 * ((R >> 2) & 3) + 4 * ((R >> 4) & 1) + (R & 3);
;         const int Rb0 = Epi::PERM ? (Epi::F32OUT ? Rf : Rw) : R, Rb1 = Epi::PERM ? (Epi::F32OUT ? Rf + 32 : Rw + 8) : R + HALF;
;         voffA[i] = (unsigned)(R * K + C) * 2u; voffB0[i] = (unsigned)(Rb0 * K + C) * 2u; voffB1[i] = (unsigned)(Rb1 * K + C) * 2u; }
;     const size_t kstep = (size_t)(BK * 2);
;     const size_t hstep = (size_t)HALF * K * 2;
;     const size_t tstep = 2 * hstep;
;     const unsigned ldsw = (unsigned)wid * 1024u;
;     const int aoff = lds_byte(wr * 64 + fr, fq * 8), boff = lds_byte(wc * 32 + fr, fq * 8);
;     ...
;     Unit cur, nxt; int ui = 0;
;     if (!S.next(0, cur)) return;
;     f32x4 acc[2][2][4][2];
; #pragma unroll
;     for (int a = 0; a < 2; ++a)
; #pragma unroll
;         for (int b = 0; b < 2; ++b)
; #pragma unroll
;             for (int m = 0; m < 4; ++m)
; #pragma unroll
;                 for (int n = 0; n < 2; ++n) acc[a][b][m][n] = (f32x4){0.f, 0.f, 0.f, 0.f};
;     bf16x8 At[4][2], B0[2][2], B1[2][2];
;     const char* cA = (const char*)g.A + (size_t)cur.pm * tstep; const char* cB = (const char*)g.Bt + (size_t)cur.pn * tstep;
;     PG8_STAGE(PG8_SB(0, 0), cB, voffB0); PG8_STAGE(PG8_SA(0, 0), cA, voffA); PG8_STAGE(PG8_SB(0, 1), cB, voffB1); PG8_STAGE(PG8_SA(0, 1), cA + hstep, voffA);
;     if (wr == 1) PG8_BAR;
;     PG8_WAIT_V(4); PG8_BAR;
;     PG8_STAGE(PG8_SB(1, 0), cB + kstep, voffB0); PG8_STAGE(PG8_SA(1, 0), cA + kstep, voffA); PG8_STAGE(PG8_SB(1, 1), cB + kstep, voffB1);
;     PG8_WAIT_V(6); PG8_BAR;
.LBB0_954:
	s_or_b64 exec, exec, s[6:7]
	s_mov_b64 s[6:7], s[0:1]
	s_waitcnt lgkmcnt(0)
	v_mov_b32_e32 v0, v202
	s_mov_b32 s8, s2
	v_mov_b32_e32 v12, v202
	s_barrier
	s_cmpk_gt_i32 s2, 0x2ff
	v_readfirstlane_b32 s52, v12
	s_cbranch_scc1 .LBB0_967
	v_lshlrev_b32_e32 v0, 4, v12
	v_add_u32_e32 v1, 0x2000, v0
	v_ashrrev_i32_e32 v2, 31, v1
	v_lshrrev_b32_e32 v2, 22, v2
	v_add_u32_e32 v2, v1, v2
	v_ashrrev_i32_e32 v13, 10, v2
	v_mul_i32_i24_e32 v2, 0x400, v13
	v_sub_u32_e32 v1, v1, v2
	v_lshrrev_b32_e32 v2, 4, v1
	v_bitop3_b32 v1, v2, v1, 32 bitop3:0x6c
	v_ashrrev_i32_e32 v2, 31, v1
	v_lshrrev_b32_e32 v2, 26, v2
	v_add_u32_e32 v2, v1, v2
	v_lshlrev_b32_e32 v3, 3, v13
	v_ashrrev_i32_e32 v14, 6, v2
	v_and_b32_e32 v3, -16, v3
	v_add_u32_e32 v3, v14, v3
	s_load_dwordx2 s[6:7], s[6:7], 0xf0
	v_lshlrev_b32_e32 v4, 2, v3
	v_and_b32_e32 v5, 3, v14
	v_and_or_b32 v4, v4, 48, v5
	v_lshlrev_b32_e32 v5, 1, v3
	v_lshrrev_b32_e32 v6, 2, v3
	v_and_b32_e32 v2, 0xc0, v2
	v_and_b32_e32 v5, 0xfffc0, v5
	v_and_b32_e32 v6, 4, v6
	v_sub_u32_e32 v1, v1, v2
	v_mov_b32_e32 v2, 1
	v_or3_b32 v4, v4, v5, v6
	v_lshlrev_b32_e32 v5, 5, v13
	v_ashrrev_i16_sdwa v1, v2, sext(v1) dst_sel:DWORD dst_unused:UNUSED_PAD src0_sel:DWORD src1_sel:BYTE_0
	v_and_b32_e32 v5, 32, v5
	v_bfe_i32 v15, v1, 0, 16
	s_waitcnt lgkmcnt(0)
	s_add_u32 s53, s6, 0x6400000
	v_add_lshl_u32 v1, v5, v15, 1
	s_addc_u32 s54, s7, 0
	v_lshl_add_u32 v128, v4, 12, v1
	v_lshl_add_u32 v132, v3, 12, v1
	v_bfe_i32 v1, v12, 27, 1
	s_add_u32 s55, s6, 0x4900000
	v_lshrrev_b32_e32 v1, 22, v1
	s_addc_u32 s56, s7, 0
	v_add_u32_e32 v1, v0, v1
	s_ashr_i32 s58, s2, 31
	v_and_b32_e32 v1, 0xfffffc00, v1
	s_lshr_b32 s8, s58, 29
	v_sub_u32_e32 v0, v0, v1
	s_add_i32 s8, s2, s8
	v_lshrrev_b32_e32 v1, 4, v0
	v_ashrrev_i32_e32 v3, 31, v12
	s_ashr_i32 s9, s8, 3
	s_and_b32 s8, s8, -8
	v_bitop3_b32 v0, v1, v0, 32 bitop3:0x6c
	v_lshrrev_b32_e32 v3, 26, v3
	s_sub_i32 s8, s2, s8
	v_ashrrev_i32_e32 v1, 31, v0
	v_add_u32_e32 v3, v12, v3
	s_lshr_b32 s10, s8, 31
	v_lshrrev_b32_e32 v1, 26, v1
	v_ashrrev_i32_e32 v17, 6, v3
	s_or_b32 s10, s10, 0x60
	v_add_u32_e32 v1, v0, v1
	v_lshlrev_b32_e32 v3, 3, v17
	s_mul_i32 s8, s10, s8
	v_ashrrev_i32_e32 v16, 6, v1
	v_and_b32_e32 v3, -16, v3
	s_add_i32 s8, s8, s9
	v_add_u32_e32 v3, v16, v3
	s_mul_hi_i32 s9, s8, 0x2aaaaaab
	v_lshlrev_b32_e32 v4, 2, v3
	v_and_b32_e32 v5, 3, v16
	s_lshr_b32 s10, s9, 31
	s_ashr_i32 s9, s9, 4
	v_and_or_b32 v4, v4, 48, v5
	v_lshlrev_b32_e32 v5, 1, v3
	v_lshrrev_b32_e32 v6, 2, v3
	v_and_b32_e32 v1, 0xc0, v1
	s_add_i32 s9, s9, s10
	v_and_b32_e32 v5, 0xfffc0, v5
	v_and_b32_e32 v6, 4, v6
	v_sub_u32_e32 v0, v0, v1
	s_lshl_b32 s10, s9, 3
	v_or3_b32 v4, v4, v5, v6
	v_lshlrev_b32_e32 v5, 5, v17
	v_ashrrev_i16_sdwa v0, v2, sext(v0) dst_sel:DWORD dst_unused:UNUSED_PAD src0_sel:DWORD src1_sel:BYTE_0
	s_sub_i32 s11, 64, s10
	s_mulk_i32 s9, 0x60
	v_and_b32_e32 v5, 32, v5
	v_bfe_i32 v18, v0, 0, 16
	s_min_u32 s11, s11, 8
	s_sub_i32 s16, s8, s9
	v_add_lshl_u32 v0, v5, v18, 1
	s_sext_i32_i8 s8, s16
	v_cvt_f32_ubyte0_e32 v2, s11
	v_lshl_add_u32 v134, v4, 12, v0
	v_cvt_f32_i32_e32 v1, s8
	v_rcp_iflag_f32_e32 v4, v2
	v_lshl_add_u32 v138, v3, 12, v0
	s_ashr_i32 s36, s52, 6
	s_ashr_i32 s8, s8, 30
	v_mul_f32_e32 v0, v1, v4
	v_trunc_f32_e32 v0, v0
	v_fma_f32 v1, -v0, v2, v1
	v_cvt_i32_f32_e32 v0, v0
	s_ashr_i32 s19, s52, 8
	s_lshl_b32 s57, s36, 10
	s_or_b32 s17, s8, 1
	v_cmp_ge_f32_e64 s[8:9], |v1|, v2
	s_and_b64 s[8:9], s[8:9], exec
	s_cselect_b32 s8, s17, 0
	v_readfirstlane_b32 s9, v0
	s_add_i32 s18, s9, s8
	s_mul_i32 s8, s18, s11
	s_sub_i32 s8, s16, s8
	s_sext_i32_i8 s8, s8
	s_add_i32 s44, s10, s8
	s_ashr_i32 s45, s44, 31
	s_bfe_i64 s[10:11], s[18:19], 0x80000
	s_lshl_b64 s[8:9], s[44:45], 20
	s_lshl_b64 s[10:11], s[10:11], 20
	s_add_u32 s48, s55, s10
	s_addc_u32 s49, s56, s11
	s_add_i32 s45, s57, 0
	s_add_i32 m0, s45, 0x10000
	v_add_u32_e32 v136, 0x8000, v134
	global_load_lds_dwordx4 v134, s[48:49]
	s_add_i32 m0, s45, 0x12000
	s_add_u32 s46, s53, s8
	global_load_lds_dwordx4 v128, s[48:49]
	s_addc_u32 s47, s54, s9
	s_mov_b32 m0, s45
	s_add_i32 s59, s45, 0x2000
	global_load_lds_dwordx4 v138, s[46:47]
	s_mov_b32 m0, s59
	v_add_u32_e32 v130, 0x8000, v128
	global_load_lds_dwordx4 v132, s[46:47]
	s_add_i32 m0, s45, 0x14000
	v_mov_b32_e32 v135, 0
	global_load_lds_dwordx4 v136, s[48:49]
	s_add_i32 m0, s45, 0x16000
	s_add_u32 s8, s46, 0x80000
	s_addc_u32 s9, s47, 0
	s_add_i32 s60, s45, 0x4000
	global_load_lds_dwordx4 v130, s[48:49]
	s_mov_b32 m0, s60
	s_add_i32 s61, s45, 0x6000
	global_load_lds_dwordx4 v138, s[8:9]
	s_mov_b32 m0, s61
	v_mov_b32_e32 v129, v135
	global_load_lds_dwordx4 v132, s[8:9]
	v_mov_b32_e32 v139, v135
	v_mov_b32_e32 v133, v135
	v_mov_b32_e32 v137, v135
	v_mov_b32_e32 v131, v135
	s_mov_b32 s62, 0
	v_lshl_add_u64 v[10:11], s[48:49], 0, v[134:135]
	v_lshl_add_u64 v[8:9], s[48:49], 0, v[128:129]
	v_lshl_add_u64 v[6:7], s[46:47], 0, v[138:139]
	v_lshl_add_u64 v[4:5], s[46:47], 0, v[132:133]
	v_lshl_add_u64 v[0:1], s[48:49], 0, v[136:137]
	s_cmp_lg_u32 s19, 1
	v_lshl_add_u64 v[2:3], s[48:49], 0, v[130:131]
	s_setprio 1
	s_cbranch_scc1 .LBB0_957
	s_barrier
	s_setprio 0

;     __device__ bool next(int i, Unit& u) const {
;         if (i >= icnt) return false;
;         const long L = (long)(i + ioff) * G + c; if (L >= nwg) return false;
; template <class Epi>
; __device__ __forceinline__ void gemm_phase(LAS unsigned char* lds, const Gemm g, const StaticOrder& S, const Epi& E) {
;     int tid = threadIdx.x; asm volatile("" : "+v"(tid));
;     const int wid = __builtin_amdgcn_readfirstlane(tid >> 6), lane = tid & 63, wr = wid >> 2, wc = wid & 3, fr = lane & 15, fq = lane >> 4;
;     const int K = g.K, nt = K / BK;
;     unsigned voffA[2], voffB0[2], voffB1[2];
; #pragma unroll
;     for (int i = 0; i < 2; ++i) { int R, C; stage_rc(tid * 16 + i * 8192, R, C);
;         const int Rw = 64 * (R >> 5) + 16 * ((R >> 2) & 3) + 4 * ((R >> 4) & 1) + (R & 3);
;         const int Rf = 64 * (R >> 5) + 8 * ((R >> 2) & 3) + 4 * ((R >> 4) & 1) + (R & 3);
;         const int Rb0 = Epi::PERM ? (Epi::F32OUT ? Rf : Rw) : R, Rb1 = Epi::PERM ? (Epi::F32OUT ? Rf + 32 : Rw + 8) : R + HALF;
;         voffA[i] = (unsigned)(R * K + C) * 2u; voffB0[i] = (unsigned)(Rb0 * K + C) * 2u; voffB1[i] = (unsigned)(Rb1 * K + C) * 2u; }
;     const size_t kstep = (size_t)(BK * 2);
;     const size_t hstep = (size_t)HALF * K * 2;
;     const size_t tstep = 2 * hstep;
;     const unsigned ldsw = (unsigned)wid * 1024u;
;     const int aoff = lds_byte(wr * 64 + fr, fq * 8), boff = lds_byte(wc * 32 + fr, fq * 8);
;     ...
;     Unit cur, nxt; int ui = 0;
;     if (!S.next(0, cur)) return;
;     f32x4 acc[2][2][4][2];
; #pragma unroll
;     for (int a = 0; a < 2; ++a)
; #pragma unroll
;         for (int b = 0; b < 2; ++b)
; #pragma unroll
;             for (int m = 0; m < 4; ++m)
; #pragma unroll
;                 for (int n = 0; n < 2; ++n) acc[a][b][m][n] = (f32x4){0.f, 0.f, 0.f, 0.f};
;     bf16x8 At[4][2], B0[2][2], B1[2][2];
;     const char* cA = (const char*)g.A + (size_t)cur.pm * tstep; const char* cB = (const char*)g.Bt + (size_t)cur.pn * tstep;
;     PG8_STAGE(PG8_SB(0, 0), cB, voffB0); PG8_STAGE(PG8_SA(0, 0), cA, voffA); PG8_STAGE(PG8_SB(0, 1), cB, voffB1); PG8_STAGE(PG8_SA(0, 1), cA + hstep, voffA);
;     if (wr == 1) PG8_BAR;
;     PG8_WAIT_V(4); PG8_BAR;
;     PG8_STAGE(PG8_SB(1, 0), cB + kstep, voffB0); PG8_STAGE(PG8_SA(1, 0), cA + kstep, voffA); PG8_STAGE(PG8_SB(1, 1), cB + kstep, voffB1);
;     PG8_WAIT_V(6); PG8_BAR;
.LBB0_1232:
	s_load_dwordx4 s[16:19], s[6:7], 0xe8
	s_and_b64 vcc, exec, s[4:5]
	s_cbranch_vccnz .LBB0_1265
	v_ashrrev_i32_e32 v1, 31, v12
	v_lshrrev_b32_e32 v1, 26, v1
	v_add_u32_e32 v1, v12, v1
	v_ashrrev_i32_e32 v13, 6, v1
	v_bfe_i32 v1, v12, 27, 1
	v_lshlrev_b32_e32 v0, 4, v12
	v_lshrrev_b32_e32 v1, 22, v1
	v_add_u32_e32 v1, v0, v1
	v_and_b32_e32 v1, 0xfffffc00, v1
	v_sub_u32_e32 v1, v0, v1
	v_lshrrev_b32_e32 v2, 4, v1
	v_bitop3_b32 v2, v2, v1, 32 bitop3:0x6c
	v_ashrrev_i32_e32 v1, 31, v1
	v_lshrrev_b32_e32 v1, 26, v1
	v_add_u32_e32 v1, v2, v1
	v_ashrrev_i32_e32 v14, 6, v1
	v_lshlrev_b32_e32 v3, 3, v13
	v_mul_i32_i24_e32 v4, 64, v14
	v_and_b32_e32 v3, -16, v3
	v_sub_u32_e32 v2, v2, v4
	v_mov_b32_e32 v4, 1
	v_add_u32_e32 v1, v14, v3
	v_lshlrev_b32_e32 v3, 5, v13
	v_ashrrev_i16_sdwa v2, v4, sext(v2) dst_sel:DWORD dst_unused:UNUSED_PAD src0_sel:DWORD src1_sel:BYTE_0
	v_and_b32_e32 v3, 32, v3
	v_bfe_i32 v15, v2, 0, 16
	v_add_lshl_u32 v3, v3, v15, 1
	v_add_u32_e32 v0, 0x2000, v0
	v_lshlrev_b32_e32 v2, 1, v1
	v_lshlrev_b32_e32 v5, 2, v1
	v_lshrrev_b32_e32 v6, 2, v1
	v_lshl_add_u32 v128, v1, 12, v3
	v_ashrrev_i32_e32 v1, 31, v0
	v_lshrrev_b32_e32 v1, 22, v1
	v_add_u32_e32 v1, v0, v1
	s_waitcnt vmcnt(1)
	v_ashrrev_i32_e32 v16, 10, v1
	v_mul_i32_i24_e32 v1, 0x400, v16
	v_and_b32_e32 v7, 3, v14
	v_sub_u32_e32 v0, v0, v1
	v_and_b32_e32 v2, 0xfffc0, v2
	v_and_b32_e32 v6, 4, v6
	v_and_or_b32 v5, v5, 48, v7
	v_lshrrev_b32_e32 v1, 4, v0
	v_or3_b32 v2, v5, v2, v6
	v_bitop3_b32 v0, v1, v0, 32 bitop3:0x6c
	s_waitcnt lgkmcnt(0)
	s_add_u32 s53, s18, 0x1ac00000
	v_lshl_add_u32 v130, v2, 12, v3
	v_ashrrev_i32_e32 v2, 31, v0
	s_addc_u32 s54, s19, 0
	v_lshrrev_b32_e32 v2, 26, v2
	s_add_u32 s55, s18, 0x5500000
	v_add_u32_e32 v2, v0, v2
	s_addc_u32 s56, s19, 0
	s_ashr_i32 s6, s52, 6
	v_lshlrev_b32_e32 v1, 3, v16
	v_ashrrev_i32_e32 v17, 6, v2
	v_and_b32_e32 v2, 0xc0, v2
	s_ashr_i32 s45, s44, 31
	s_ashr_i32 s43, s42, 31
	v_and_b32_e32 v1, -16, v1
	v_sub_u32_e32 v0, v0, v2
	s_ashr_i32 s7, s52, 8
	s_lshl_b32 s57, s6, 10
	s_lshl_b64 s[8:9], s[44:45], 20
	s_lshl_b64 s[10:11], s[42:43], 20
	v_add_u32_e32 v1, v17, v1
	v_ashrrev_i16_sdwa v0, v4, sext(v0) dst_sel:DWORD dst_unused:UNUSED_PAD src0_sel:DWORD src1_sel:BYTE_0
	s_add_u32 s48, s55, s10
	v_lshlrev_b32_e32 v3, 5, v16
	v_bfe_i32 v18, v0, 0, 16
	v_lshlrev_b32_e32 v0, 1, v1
	v_lshlrev_b32_e32 v2, 2, v1
	v_lshrrev_b32_e32 v4, 2, v1
	v_and_b32_e32 v5, 3, v17
	s_addc_u32 s49, s56, s11
	s_add_i32 s45, s57, 0
	v_and_b32_e32 v3, 32, v3
	v_and_b32_e32 v0, 0xfffc0, v0
	v_and_b32_e32 v4, 4, v4
	v_and_or_b32 v2, v2, 48, v5
	s_add_i32 m0, s45, 0x10000
	v_or3_b32 v0, v2, v0, v4
	v_add_lshl_u32 v2, v3, v18, 1
	global_load_lds_dwordx4 v130, s[48:49]
	s_add_i32 m0, s45, 0x12000
	v_lshl_add_u32 v136, v0, 12, v2
	s_add_u32 s46, s53, s8
	global_load_lds_dwordx4 v136, s[48:49]
	s_addc_u32 s47, s54, s9
	s_mov_b32 m0, s45
	s_add_i32 s58, s45, 0x2000
	v_lshl_add_u32 v134, v1, 12, v2
	global_load_lds_dwordx4 v128, s[46:47]
	s_mov_b32 m0, s58
	v_add_u32_e32 v132, 0x8000, v130
	global_load_lds_dwordx4 v134, s[46:47]
	s_add_i32 m0, s45, 0x14000
	v_add_u32_e32 v138, 0x8000, v136
	global_load_lds_dwordx4 v132, s[48:49]
	s_add_i32 m0, s45, 0x16000
	s_add_u32 s8, s46, 0x80000
	s_addc_u32 s9, s47, 0
	s_add_i32 s59, s45, 0x4000
	global_load_lds_dwordx4 v138, s[48:49]
	s_mov_b32 m0, s59
	s_add_i32 s60, s45, 0x6000
	global_load_lds_dwordx4 v128, s[8:9]
	s_mov_b32 m0, s60
	v_mov_b32_e32 v131, 0
	global_load_lds_dwordx4 v134, s[8:9]
	v_mov_b32_e32 v137, v131
	v_mov_b32_e32 v129, v131
	v_mov_b32_e32 v135, v131
	v_mov_b32_e32 v133, v131
	v_mov_b32_e32 v139, v131
	s_mov_b32 s61, 0
	v_lshl_add_u64 v[10:11], s[48:49], 0, v[130:131]
	v_lshl_add_u64 v[8:9], s[48:49], 0, v[136:137]
	v_lshl_add_u64 v[6:7], s[46:47], 0, v[128:129]
	v_lshl_add_u64 v[4:5], s[46:47], 0, v[134:135]
	v_lshl_add_u64 v[0:1], s[48:49], 0, v[132:133]
	s_cmp_lg_u32 s7, 1
	v_lshl_add_u64 v[2:3], s[48:49], 0, v[138:139]
	s_setprio 1
	s_cbranch_scc1 .LBB0_1235
	s_barrier
	s_setprio 0

;     __device__ bool next(int i, Unit& u) const {
;         if (i >= icnt) return false;
;         const long L = (long)(i + ioff) * G + c; if (L >= nwg) return false;
; template <class Epi>
; __device__ __forceinline__ void gemm_phase(LAS unsigned char* lds, const Gemm g, const StaticOrder& S, const Epi& E) {
;     int tid = threadIdx.x; asm volatile("" : "+v"(tid));
;     const int wid = __builtin_amdgcn_readfirstlane(tid >> 6), lane = tid & 63, wr = wid >> 2, wc = wid & 3, fr = lane & 15, fq = lane >> 4;
;     const int K = g.K, nt = K / BK;
;     unsigned voffA[2], voffB0[2], voffB1[2];
; #pragma unroll
;     for (int i = 0; i < 2; ++i) { int R, C; stage_rc(tid * 16 + i * 8192, R, C);
;         const int Rw = 64 * (R >> 5) + 16 * ((R >> 2) & 3) + 4 * ((R >> 4) & 1) + (R & 3);
;         const int Rf = 64 * (R >> 5) + 8 * ((R >> 2) & 3) + 4 * ((R >> 4) & 1) + (R & 3);
;         const int Rb0 = Epi::PERM ? (Epi::F32OUT ? Rf : Rw) : R, Rb1 = Epi::PERM ? (Epi::F32OUT ? Rf + 32 : Rw + 8) : R + HALF;
;         voffA[i] = (unsigned)(R * K + C) * 2u; voffB0[i] = (unsigned)(Rb0 * K + C) * 2u; voffB1[i] = (unsigned)(Rb1 * K + C) * 2u; }
;     const size_t kstep = (size_t)(BK * 2);
;     const size_t hstep = (size_t)HALF * K * 2;
;     const size_t tstep = 2 * hstep;
;     const unsigned ldsw = (unsigned)wid * 1024u;
;     const int aoff = lds_byte(wr * 64 + fr, fq * 8), boff = lds_byte(wc * 32 + fr, fq * 8);
;     ...
;     Unit cur, nxt; int ui = 0;
;     if (!S.next(0, cur)) return;
;     f32x4 acc[2][2][4][2];
; #pragma unroll
;     for (int a = 0; a < 2; ++a)
; #pragma unroll
;         for (int b = 0; b < 2; ++b)
; #pragma unroll
;             for (int m = 0; m < 4; ++m)
; #pragma unroll
;                 for (int n = 0; n < 2; ++n) acc[a][b][m][n] = (f32x4){0.f, 0.f, 0.f, 0.f};
;     bf16x8 At[4][2], B0[2][2], B1[2][2];
;     const char* cA = (const char*)g.A + (size_t)cur.pm * tstep; const char* cB = (const char*)g.Bt + (size_t)cur.pn * tstep;
;     PG8_STAGE(PG8_SB(0, 0), cB, voffB0); PG8_STAGE(PG8_SA(0, 0), cA, voffA); PG8_STAGE(PG8_SB(0, 1), cB, voffB1); PG8_STAGE(PG8_SA(0, 1), cA + hstep, voffA);
;     if (wr == 1) PG8_BAR;
;     PG8_WAIT_V(4); PG8_BAR;
;     PG8_STAGE(PG8_SB(1, 0), cB + kstep, voffB0); PG8_STAGE(PG8_SA(1, 0), cA + kstep, voffA); PG8_STAGE(PG8_SB(1, 1), cB + kstep, voffB1);
;     PG8_WAIT_V(6); PG8_BAR;
.LBB0_1267:
	s_and_b64 vcc, exec, s[4:5]
	s_cbranch_vccnz .LBB0_1297
	v_bfe_i32 v2, v12, 27, 1
	v_lshlrev_b32_e32 v0, 4, v12
	v_lshrrev_b32_e32 v2, 22, v2
	v_add_u32_e32 v2, v0, v2
	v_and_b32_e32 v2, 0xfffffc00, v2
	v_sub_u32_e32 v2, v0, v2
	v_ashrrev_i32_e32 v1, 31, v12
	v_lshrrev_b32_e32 v3, 4, v2
	v_lshrrev_b32_e32 v1, 26, v1
	v_bitop3_b32 v2, v3, v2, 32 bitop3:0x6c
	v_add_u32_e32 v1, v12, v1
	v_ashrrev_i32_e32 v4, 31, v2
	v_ashrrev_i32_e32 v1, 6, v1
	v_lshrrev_b32_e32 v4, 26, v4
	v_lshlrev_b32_e32 v3, 3, v1
	v_add_u32_e32 v4, v2, v4
	v_and_b32_e32 v3, -16, v3
	v_ashrrev_i32_e32 v5, 6, v4
	v_and_b32_e32 v4, 0xc0, v4
	v_add_u32_e32 v3, v5, v3
	v_sub_u32_e32 v2, v2, v4
	v_mov_b32_e32 v4, 1
	v_lshlrev_b32_e32 v1, 5, v1
	v_ashrrev_i16_sdwa v2, v4, sext(v2) dst_sel:DWORD dst_unused:UNUSED_PAD src0_sel:DWORD src1_sel:BYTE_0
	v_lshlrev_b32_e32 v6, 1, v3
	v_lshlrev_b32_e32 v7, 2, v3
	v_lshrrev_b32_e32 v8, 2, v3
	v_and_b32_e32 v5, 3, v5
	v_and_b32_e32 v1, 32, v1
	v_bfe_i32 v2, v2, 0, 16
	v_and_b32_e32 v6, 0x7fffc0, v6
	v_and_b32_e32 v8, 4, v8
	v_and_or_b32 v5, v7, 48, v5
	v_or3_b32 v5, v5, v6, v8
	v_add_lshl_u32 v1, v1, v2, 1
	v_add_u32_e32 v0, 0x2000, v0
	v_lshl_add_u32 v128, v3, 9, v1
	v_lshl_add_u32 v130, v5, 9, v1
	v_ashrrev_i32_e32 v1, 31, v0
	v_lshrrev_b32_e32 v1, 22, v1
	s_load_dwordx2 s[6:7], s[6:7], 0xf0
	v_add_u32_e32 v1, v0, v1
	v_ashrrev_i32_e32 v1, 10, v1
	v_mul_i32_i24_e32 v2, 0x400, v1
	v_sub_u32_e32 v0, v0, v2
	v_lshrrev_b32_e32 v2, 4, v0
	s_waitcnt lgkmcnt(0)
	s_add_u32 s55, s6, 0x1f800000
	v_bitop3_b32 v0, v2, v0, 32 bitop3:0x6c
	s_addc_u32 s56, s7, 0
	v_ashrrev_i32_e32 v3, 31, v0
	s_add_u32 s57, s6, 0x4800000
	v_lshrrev_b32_e32 v3, 26, v3
	s_addc_u32 s58, s7, 0
	s_ashr_i32 s8, s54, 6
	v_lshlrev_b32_e32 v2, 3, v1
	v_add_u32_e32 v3, v0, v3
	s_ashr_i32 s41, s40, 31
	s_ashr_i32 s39, s38, 31
	v_and_b32_e32 v2, -16, v2
	v_ashrrev_i32_e32 v5, 6, v3
	v_and_b32_e32 v3, 0xc0, v3
	s_ashr_i32 s9, s54, 8
	s_lshl_b32 s59, s8, 10
	s_lshl_b64 s[10:11], s[40:41], 17
	s_lshl_b64 s[16:17], s[38:39], 17
	v_add_u32_e32 v2, v5, v2
	v_sub_u32_e32 v0, v0, v3
	s_add_u32 s42, s57, s16
	v_lshlrev_b32_e32 v1, 5, v1
	v_ashrrev_i16_sdwa v0, v4, sext(v0) dst_sel:DWORD dst_unused:UNUSED_PAD src0_sel:DWORD src1_sel:BYTE_0
	v_lshlrev_b32_e32 v3, 1, v2
	v_lshlrev_b32_e32 v4, 2, v2
	v_lshrrev_b32_e32 v6, 2, v2
	v_and_b32_e32 v5, 3, v5
	s_addc_u32 s43, s58, s17
	s_add_i32 s41, s59, 0
	v_and_b32_e32 v1, 32, v1
	v_bfe_i32 v0, v0, 0, 16
	v_and_b32_e32 v3, 0x7fffc0, v3
	v_and_b32_e32 v6, 4, v6
	v_and_or_b32 v4, v4, 48, v5
	s_add_i32 m0, s41, 0x10000
	v_or3_b32 v3, v4, v3, v6
	v_add_lshl_u32 v0, v1, v0, 1
	global_load_lds_dwordx4 v130, s[42:43]
	s_add_i32 m0, s41, 0x12000
	v_lshl_add_u32 v136, v3, 9, v0
	s_add_u32 s44, s55, s10
	global_load_lds_dwordx4 v136, s[42:43]
	s_addc_u32 s45, s56, s11
	s_mov_b32 m0, s41
	s_add_i32 s60, s41, 0x2000
	v_lshl_add_u32 v134, v2, 9, v0
	global_load_lds_dwordx4 v128, s[44:45]
	s_mov_b32 m0, s60
	v_add_u32_e32 v132, 0x1000, v130
	global_load_lds_dwordx4 v134, s[44:45]
	s_add_i32 m0, s41, 0x14000
	v_add_u32_e32 v138, 0x1000, v136
	global_load_lds_dwordx4 v132, s[42:43]
	s_add_i32 m0, s41, 0x16000
	s_add_u32 s10, s44, 0x10000
	s_addc_u32 s11, s45, 0
	s_add_i32 s61, s41, 0x4000
	global_load_lds_dwordx4 v138, s[42:43]
	s_mov_b32 m0, s61
	s_add_i32 s62, s41, 0x6000
	global_load_lds_dwordx4 v128, s[10:11]
	s_mov_b32 m0, s62
	v_mov_b32_e32 v131, 0
	global_load_lds_dwordx4 v134, s[10:11]
	v_mov_b32_e32 v137, v131
	v_mov_b32_e32 v129, v131
	v_mov_b32_e32 v135, v131
	v_mov_b32_e32 v133, v131
	v_mov_b32_e32 v139, v131
	s_mov_b32 s63, 0
	v_lshl_add_u64 v[10:11], s[42:43], 0, v[130:131]
	v_lshl_add_u64 v[8:9], s[42:43], 0, v[136:137]
	v_lshl_add_u64 v[6:7], s[44:45], 0, v[128:129]
	v_lshl_add_u64 v[4:5], s[44:45], 0, v[134:135]
	v_lshl_add_u64 v[0:1], s[42:43], 0, v[132:133]
	s_cmp_lg_u32 s9, 1
	v_lshl_add_u64 v[2:3], s[42:43], 0, v[138:139]
	s_setprio 1
	s_cbranch_scc1 .LBB0_1270
	s_barrier
	s_setprio 0

;     __device__ bool next(int i, Unit& u) const {
;         if (i >= icnt) return false;
;         const long L = (long)(i + ioff) * G + c; if (L >= nwg) return false;
; template <class Epi>
; __device__ __forceinline__ void gemm_phase(LAS unsigned char* lds, const Gemm g, const StaticOrder& S, const Epi& E) {
;     int tid = threadIdx.x; asm volatile("" : "+v"(tid));
;     const int wid = __builtin_amdgcn_readfirstlane(tid >> 6), lane = tid & 63, wr = wid >> 2, wc = wid & 3, fr = lane & 15, fq = lane >> 4;
;     const int K = g.K, nt = K / BK;
;     unsigned voffA[2], voffB0[2], voffB1[2];
; #pragma unroll
;     for (int i = 0; i < 2; ++i) { int R, C; stage_rc(tid * 16 + i * 8192, R, C);
;         const int Rw = 64 * (R >> 5) + 16 * ((R >> 2) & 3) + 4 * ((R >> 4) & 1) + (R & 3);
;         const int Rf = 64 * (R >> 5) + 8 * ((R >> 2) & 3) + 4 * ((R >> 4) & 1) + (R & 3);
;         const int Rb0 = Epi::PERM ? (Epi::F32OUT ? Rf : Rw) : R, Rb1 = Epi::PERM ? (Epi::F32OUT ? Rf + 32 : Rw + 8) : R + HALF;
;         voffA[i] = (unsigned)(R * K + C) * 2u; voffB0[i] = (unsigned)(Rb0 * K + C) * 2u; voffB1[i] = (unsigned)(Rb1 * K + C) * 2u; }
;     const size_t kstep = (size_t)(BK * 2);
;     const size_t hstep = (size_t)HALF * K * 2;
;     const size_t tstep = 2 * hstep;
;     const unsigned ldsw = (unsigned)wid * 1024u;
;     const int aoff = lds_byte(wr * 64 + fr, fq * 8), boff = lds_byte(wc * 32 + fr, fq * 8);
;     ...
;     Unit cur, nxt; int ui = 0;
;     if (!S.next(0, cur)) return;
;     f32x4 acc[2][2][4][2];
; #pragma unroll
;     for (int a = 0; a < 2; ++a)
; #pragma unroll
;         for (int b = 0; b < 2; ++b)
; #pragma unroll
;             for (int m = 0; m < 4; ++m)
; #pragma unroll
;                 for (int n = 0; n < 2; ++n) acc[a][b][m][n] = (f32x4){0.f, 0.f, 0.f, 0.f};
;     bf16x8 At[4][2], B0[2][2], B1[2][2];
;     const char* cA = (const char*)g.A + (size_t)cur.pm * tstep; const char* cB = (const char*)g.Bt + (size_t)cur.pn * tstep;
;     PG8_STAGE(PG8_SB(0, 0), cB, voffB0); PG8_STAGE(PG8_SA(0, 0), cA, voffA); PG8_STAGE(PG8_SB(0, 1), cB, voffB1); PG8_STAGE(PG8_SA(0, 1), cA + hstep, voffA);
;     if (wr == 1) PG8_BAR;
;     PG8_WAIT_V(4); PG8_BAR;
;     PG8_STAGE(PG8_SB(1, 0), cB + kstep, voffB0); PG8_STAGE(PG8_SA(1, 0), cA + kstep, voffA); PG8_STAGE(PG8_SB(1, 1), cB + kstep, voffB1);
;     PG8_WAIT_V(6); PG8_BAR;
.LBB0_1354:
	v_ashrrev_i32_e32 v1, 31, v12
	v_lshrrev_b32_e32 v1, 26, v1
	v_add_u32_e32 v1, v12, v1
	v_ashrrev_i32_e32 v13, 6, v1
	v_bfe_i32 v1, v12, 27, 1
	v_lshlrev_b32_e32 v0, 4, v12
	v_lshrrev_b32_e32 v1, 22, v1
	v_add_u32_e32 v1, v0, v1
	v_and_b32_e32 v1, 0xfffffc00, v1
	v_sub_u32_e32 v1, v0, v1
	v_lshrrev_b32_e32 v2, 4, v1
	v_bitop3_b32 v1, v2, v1, 32 bitop3:0x6c
	v_ashrrev_i32_e32 v3, 31, v1
	v_lshrrev_b32_e32 v3, 26, v3
	v_add_u32_e32 v3, v1, v3
	v_lshlrev_b32_e32 v2, 3, v13
	v_ashrrev_i32_e32 v14, 6, v3
	v_and_b32_e32 v3, 0xc0, v3
	v_and_b32_e32 v2, -16, v2
	v_sub_u32_e32 v1, v1, v3
	v_mov_b32_e32 v3, 1
	v_add_u32_e32 v2, v14, v2
	v_ashrrev_i16_sdwa v1, v3, sext(v1) dst_sel:DWORD dst_unused:UNUSED_PAD src0_sel:DWORD src1_sel:BYTE_0
	s_ashr_i32 s6, s17, 3
	v_lshlrev_b32_e32 v4, 5, v13
	v_bfe_i32 v15, v1, 0, 16
	v_lshlrev_b32_e32 v1, 1, v2
	v_lshlrev_b32_e32 v5, 2, v2
	v_lshrrev_b32_e32 v6, 2, v2
	v_and_b32_e32 v7, 3, v14
	v_and_b32_e32 v4, 32, v4
	v_and_b32_e32 v1, 0xfffc0, v1
	v_and_b32_e32 v6, 4, v6
	v_and_or_b32 v5, v5, 48, v7
	s_add_i32 s6, s16, s6
	v_or3_b32 v1, v5, v1, v6
	v_add_lshl_u32 v4, v4, v15, 1
	v_add_u32_e32 v0, 0x2000, v0
	s_ashr_i32 s12, s6, 31
	v_lshl_add_u32 v130, v1, 12, v4
	v_ashrrev_i32_e32 v1, 31, v0
	s_lshr_b32 s12, s12, 24
	v_lshrrev_b32_e32 v1, 22, v1
	s_add_i32 s12, s6, s12
	v_add_u32_e32 v1, v0, v1
	s_ashr_i32 s13, s12, 8
	s_and_b32 s12, s12, 0xffffff00
	v_ashrrev_i32_e32 v16, 10, v1
	s_sub_i32 s12, s6, s12
	v_mul_i32_i24_e32 v1, 0x400, v16
	s_sext_i32_i16 s6, s12
	v_sub_u32_e32 v0, v0, v1
	s_bfe_u32 s6, s6, 0x3001c
	v_lshrrev_b32_e32 v1, 4, v0
	s_add_i32 s16, s12, s6
	v_bitop3_b32 v0, v1, v0, 32 bitop3:0x6c
	s_sext_i32_i16 s6, s16
	s_and_b32 s16, s16, 0xfff8
	v_lshl_add_u32 v128, v2, 12, v4
	v_ashrrev_i32_e32 v2, 31, v0
	s_sub_i32 s12, s12, s16
	v_lshrrev_b32_e32 v2, 26, v2
	s_lshl_b32 s13, s13, 3
	s_sext_i32_i16 s12, s12
	s_ashr_i32 s7, s44, 6
	v_add_u32_e32 v2, v0, v2
	s_lshr_b32 s6, s6, 3
	s_add_i32 s36, s13, s12
	v_lshlrev_b32_e32 v1, 3, v16
	v_ashrrev_i32_e32 v17, 6, v2
	v_and_b32_e32 v2, 0xc0, v2
	s_ashr_i32 s37, s36, 31
	s_bfe_i64 s[16:17], s[6:7], 0x100000
	v_and_b32_e32 v1, -16, v1
	v_sub_u32_e32 v0, v0, v2
	s_ashr_i32 s18, s44, 8
	s_lshl_b32 s46, s7, 10
	s_lshl_b64 s[12:13], s[36:37], 20
	s_lshl_b64 s[16:17], s[16:17], 20
	v_add_u32_e32 v1, v17, v1
	v_ashrrev_i16_sdwa v0, v3, sext(v0) dst_sel:DWORD dst_unused:UNUSED_PAD src0_sel:DWORD src1_sel:BYTE_0
	s_waitcnt lgkmcnt(0)
	s_add_u32 s40, s10, s16
	v_lshlrev_b32_e32 v4, 5, v16
	v_bfe_i32 v18, v0, 0, 16
	v_lshlrev_b32_e32 v0, 1, v1
	v_lshlrev_b32_e32 v2, 2, v1
	v_lshrrev_b32_e32 v3, 2, v1
	v_and_b32_e32 v5, 3, v17
	s_addc_u32 s41, s11, s17
	s_add_i32 s37, s46, 0
	v_and_b32_e32 v4, 32, v4
	v_and_b32_e32 v0, 0xfffc0, v0
	v_and_b32_e32 v3, 4, v3
	v_and_or_b32 v2, v2, 48, v5
	s_add_i32 m0, s37, 0x10000
	v_or3_b32 v0, v2, v0, v3
	v_add_lshl_u32 v2, v4, v18, 1
	global_load_lds_dwordx4 v130, s[40:41]
	s_add_i32 m0, s37, 0x12000
	v_lshl_add_u32 v136, v0, 12, v2
	s_add_u32 s38, s8, s12
	global_load_lds_dwordx4 v136, s[40:41]
	s_addc_u32 s39, s9, s13
	s_mov_b32 m0, s37
	s_add_i32 s47, s37, 0x2000
	v_lshl_add_u32 v134, v1, 12, v2
	global_load_lds_dwordx4 v128, s[38:39]
	s_mov_b32 m0, s47
	v_add_u32_e32 v132, 0x8000, v130
	global_load_lds_dwordx4 v134, s[38:39]
	s_add_i32 m0, s37, 0x14000
	v_add_u32_e32 v138, 0x8000, v136
	global_load_lds_dwordx4 v132, s[40:41]
	s_add_i32 m0, s37, 0x16000
	s_add_u32 s12, s38, 0x80000
	s_addc_u32 s13, s39, 0
	s_add_i32 s48, s37, 0x4000
	global_load_lds_dwordx4 v138, s[40:41]
	s_mov_b32 m0, s48
	s_add_i32 s49, s37, 0x6000
	global_load_lds_dwordx4 v128, s[12:13]
	s_mov_b32 m0, s49
	v_mov_b32_e32 v131, 0
	global_load_lds_dwordx4 v134, s[12:13]
	v_mov_b32_e32 v137, v131
	v_mov_b32_e32 v129, v131
	v_mov_b32_e32 v135, v131
	v_mov_b32_e32 v133, v131
	v_mov_b32_e32 v139, v131
	s_mov_b32 s50, 0
	v_lshl_add_u64 v[10:11], s[40:41], 0, v[130:131]
	v_lshl_add_u64 v[8:9], s[40:41], 0, v[136:137]
	v_lshl_add_u64 v[6:7], s[38:39], 0, v[128:129]
	v_lshl_add_u64 v[4:5], s[38:39], 0, v[134:135]
	v_lshl_add_u64 v[0:1], s[40:41], 0, v[132:133]
	s_cmp_lg_u32 s18, 1
	v_lshl_add_u64 v[2:3], s[40:41], 0, v[138:139]
	s_setprio 1
	s_cbranch_scc1 .LBB0_1356
	s_barrier
	s_setprio 0

;     __device__ bool next(int i, Unit& u) const {
;         if (i >= icnt) return false;
;         const long L = (long)(i + ioff) * G + c; if (L >= nwg) return false;
; template <class Epi>
; __device__ __forceinline__ void gemm_phase(LAS unsigned char* lds, const Gemm g, const StaticOrder& S, const Epi& E) {
;     int tid = threadIdx.x; asm volatile("" : "+v"(tid));
;     const int wid = __builtin_amdgcn_readfirstlane(tid >> 6), lane = tid & 63, wr = wid >> 2, wc = wid & 3, fr = lane & 15, fq = lane >> 4;
;     const int K = g.K, nt = K / BK;
;     unsigned voffA[2], voffB0[2], voffB1[2];
; #pragma unroll
;     for (int i = 0; i < 2; ++i) { int R, C; stage_rc(tid * 16 + i * 8192, R, C);
;         const int Rw = 64 * (R >> 5) + 16 * ((R >> 2) & 3) + 4 * ((R >> 4) & 1) + (R & 3);
;         const int Rf = 64 * (R >> 5) + 8 * ((R >> 2) & 3) + 4 * ((R >> 4) & 1) + (R & 3);
;         const int Rb0 = Epi::PERM ? (Epi::F32OUT ? Rf : Rw) : R, Rb1 = Epi::PERM ? (Epi::F32OUT ? Rf + 32 : Rw + 8) : R + HALF;
;         voffA[i] = (unsigned)(R * K + C) * 2u; voffB0[i] = (unsigned)(Rb0 * K + C) * 2u; voffB1[i] = (unsigned)(Rb1 * K + C) * 2u; }
;     const size_t kstep = (size_t)(BK * 2);
;     const size_t hstep = (size_t)HALF * K * 2;
;     const size_t tstep = 2 * hstep;
;     const unsigned ldsw = (unsigned)wid * 1024u;
;     const int aoff = lds_byte(wr * 64 + fr, fq * 8), boff = lds_byte(wc * 32 + fr, fq * 8);
;     ...
;     Unit cur, nxt; int ui = 0;
;     if (!S.next(0, cur)) return;
;     f32x4 acc[2][2][4][2];
; #pragma unroll
;     for (int a = 0; a < 2; ++a)
; #pragma unroll
;         for (int b = 0; b < 2; ++b)
; #pragma unroll
;             for (int m = 0; m < 4; ++m)
; #pragma unroll
;                 for (int n = 0; n < 2; ++n) acc[a][b][m][n] = (f32x4){0.f, 0.f, 0.f, 0.f};
;     bf16x8 At[4][2], B0[2][2], B1[2][2];
;     const char* cA = (const char*)g.A + (size_t)cur.pm * tstep; const char* cB = (const char*)g.Bt + (size_t)cur.pn * tstep;
;     PG8_STAGE(PG8_SB(0, 0), cB, voffB0); PG8_STAGE(PG8_SA(0, 0), cA, voffA); PG8_STAGE(PG8_SB(0, 1), cB, voffB1); PG8_STAGE(PG8_SA(0, 1), cA + hstep, voffA);
;     if (wr == 1) PG8_BAR;
;     PG8_WAIT_V(4); PG8_BAR;
;     PG8_STAGE(PG8_SB(1, 0), cB + kstep, voffB0); PG8_STAGE(PG8_SA(1, 0), cA + kstep, voffA); PG8_STAGE(PG8_SB(1, 1), cB + kstep, voffB1);
;     PG8_WAIT_V(6); PG8_BAR;
.LBB0_1428:
	s_load_dwordx4 s[16:19], s[6:7], 0xe8
	s_and_b64 vcc, exec, s[4:5]
	s_cbranch_vccnz .LBB0_1534
	v_ashrrev_i32_e32 v1, 31, v12
	v_lshrrev_b32_e32 v1, 26, v1
	v_add_u32_e32 v1, v12, v1
	v_ashrrev_i32_e32 v13, 6, v1
	v_bfe_i32 v1, v12, 27, 1
	v_lshlrev_b32_e32 v0, 4, v12
	v_lshrrev_b32_e32 v1, 22, v1
	v_add_u32_e32 v1, v0, v1
	v_and_b32_e32 v1, 0xfffffc00, v1
	v_sub_u32_e32 v1, v0, v1
	v_lshrrev_b32_e32 v2, 4, v1
	v_bitop3_b32 v1, v2, v1, 32 bitop3:0x6c
	v_ashrrev_i32_e32 v3, 31, v1
	v_lshrrev_b32_e32 v3, 26, v3
	v_add_u32_e32 v3, v1, v3
	v_lshlrev_b32_e32 v2, 3, v13
	v_ashrrev_i32_e32 v14, 6, v3
	v_and_b32_e32 v3, 0xc0, v3
	v_and_b32_e32 v2, -16, v2
	v_sub_u32_e32 v1, v1, v3
	v_mov_b32_e32 v3, 1
	v_add_u32_e32 v2, v14, v2
	v_ashrrev_i16_sdwa v1, v3, sext(v1) dst_sel:DWORD dst_unused:UNUSED_PAD src0_sel:DWORD src1_sel:BYTE_0
	v_lshlrev_b32_e32 v4, 5, v13
	v_bfe_i32 v15, v1, 0, 16
	v_lshlrev_b32_e32 v1, 1, v2
	v_lshlrev_b32_e32 v5, 2, v2
	v_lshrrev_b32_e32 v6, 2, v2
	v_and_b32_e32 v7, 3, v14
	v_and_b32_e32 v4, 32, v4
	v_and_b32_e32 v1, 0x3ffc0, v1
	v_and_b32_e32 v6, 4, v6
	v_and_or_b32 v5, v5, 48, v7
	v_or3_b32 v1, v5, v1, v6
	v_add_lshl_u32 v4, v4, v15, 1
	v_add_u32_e32 v0, 0x2000, v0
	v_lshl_add_u32 v138, v1, 14, v4
	v_ashrrev_i32_e32 v1, 31, v0
	v_lshrrev_b32_e32 v1, 22, v1
	v_add_u32_e32 v1, v0, v1
	v_ashrrev_i32_e32 v16, 10, v1
	v_mul_i32_i24_e32 v1, 0x400, v16
	v_sub_u32_e32 v0, v0, v1
	v_lshrrev_b32_e32 v1, 4, v0
	v_bitop3_b32 v0, v1, v0, 32 bitop3:0x6c
	s_waitcnt lgkmcnt(0)
	s_add_u32 s49, s18, 0xec00000
	v_lshl_add_u32 v136, v2, 14, v4
	v_ashrrev_i32_e32 v2, 31, v0
	s_addc_u32 s50, s19, 0
	v_lshrrev_b32_e32 v2, 26, v2
	s_add_u32 s51, s18, 0x2000000
	v_add_u32_e32 v2, v0, v2
	s_addc_u32 s52, s19, 0
	s_ashr_i32 s6, s48, 6
	v_lshlrev_b32_e32 v1, 3, v16
	v_ashrrev_i32_e32 v17, 6, v2
	v_and_b32_e32 v2, 0xc0, v2
	s_ashr_i32 s11, s10, 31
	s_ashr_i32 s9, s8, 31
	v_and_b32_e32 v1, -16, v1
	v_sub_u32_e32 v0, v0, v2
	s_ashr_i32 s7, s48, 8
	s_lshl_b32 s53, s6, 10
	s_lshl_b64 s[12:13], s[10:11], 22
	s_lshl_b64 s[26:27], s[8:9], 22
	v_add_u32_e32 v1, v17, v1
	v_ashrrev_i16_sdwa v0, v3, sext(v0) dst_sel:DWORD dst_unused:UNUSED_PAD src0_sel:DWORD src1_sel:BYTE_0
	s_add_u32 s44, s51, s26
	v_lshlrev_b32_e32 v4, 5, v16
	v_bfe_i32 v18, v0, 0, 16
	v_lshlrev_b32_e32 v0, 1, v1
	v_lshlrev_b32_e32 v2, 2, v1
	v_lshrrev_b32_e32 v3, 2, v1
	v_and_b32_e32 v5, 3, v17
	s_addc_u32 s45, s52, s27
	s_add_i32 s54, s53, 0
	v_and_b32_e32 v4, 32, v4
	v_and_b32_e32 v0, 0x3ffc0, v0
	v_and_b32_e32 v3, 4, v3
	v_and_or_b32 v2, v2, 48, v5
	s_add_i32 m0, s54, 0x10000
	v_or3_b32 v0, v2, v0, v3
	v_add_lshl_u32 v2, v4, v18, 1
	global_load_lds_dwordx4 v138, s[44:45]
	s_add_i32 m0, s54, 0x12000
	v_lshl_add_u32 v144, v0, 14, v2
	s_add_u32 s42, s49, s12
	global_load_lds_dwordx4 v144, s[44:45]
	s_addc_u32 s43, s50, s13
	s_mov_b32 m0, s54
	s_add_i32 s55, s54, 0x2000
	v_lshl_add_u32 v142, v1, 14, v2
	global_load_lds_dwordx4 v136, s[42:43]
	s_mov_b32 m0, s55
	v_add_u32_e32 v140, 0x20000, v138
	global_load_lds_dwordx4 v142, s[42:43]
	s_add_i32 m0, s54, 0x14000
	v_add_u32_e32 v146, 0x20000, v144
	global_load_lds_dwordx4 v140, s[44:45]
	s_add_i32 m0, s54, 0x16000
	s_add_u32 s12, s42, 0x200000
	s_addc_u32 s13, s43, 0
	s_add_i32 s56, s54, 0x4000
	global_load_lds_dwordx4 v146, s[44:45]
	s_mov_b32 m0, s56
	s_add_i32 s57, s54, 0x6000
	global_load_lds_dwordx4 v136, s[12:13]
	s_mov_b32 m0, s57
	v_mov_b32_e32 v139, 0
	global_load_lds_dwordx4 v142, s[12:13]
	v_mov_b32_e32 v145, v139
	v_mov_b32_e32 v137, v139
	v_mov_b32_e32 v143, v139
	v_mov_b32_e32 v141, v139
	v_mov_b32_e32 v147, v139
	s_movk_i32 s58, 0x2000
	s_mov_b32 s59, 0
	v_lshl_add_u64 v[10:11], s[44:45], 0, v[138:139]
	v_lshl_add_u64 v[8:9], s[44:45], 0, v[144:145]
	v_lshl_add_u64 v[6:7], s[42:43], 0, v[136:137]
	v_lshl_add_u64 v[4:5], s[42:43], 0, v[142:143]
	v_lshl_add_u64 v[0:1], s[44:45], 0, v[140:141]
	s_cmp_lg_u32 s7, 1
	v_lshl_add_u64 v[2:3], s[44:45], 0, v[146:147]
	s_setprio 1
	s_cbranch_scc1 .LBB0_1431
	s_barrier
	s_setprio 0

;     __device__ bool next(int i, Unit& u) const {
;         if (i >= icnt) return false;
;         const long L = (long)(i + ioff) * G + c; if (L >= nwg) return false;
; template <class Epi>
; __device__ __forceinline__ void gemm_phase(LAS unsigned char* lds, const Gemm g, const StaticOrder& S, const Epi& E) {
;     int tid = threadIdx.x; asm volatile("" : "+v"(tid));
;     const int wid = __builtin_amdgcn_readfirstlane(tid >> 6), lane = tid & 63, wr = wid >> 2, wc = wid & 3, fr = lane & 15, fq = lane >> 4;
;     const int K = g.K, nt = K / BK;
;     unsigned voffA[2], voffB0[2], voffB1[2];
; #pragma unroll
;     for (int i = 0; i < 2; ++i) { int R, C; stage_rc(tid * 16 + i * 8192, R, C);
;         const int Rw = 64 * (R >> 5) + 16 * ((R >> 2) & 3) + 4 * ((R >> 4) & 1) + (R & 3);
;         const int Rf = 64 * (R >> 5) + 8 * ((R >> 2) & 3) + 4 * ((R >> 4) & 1) + (R & 3);
;         const int Rb0 = Epi::PERM ? (Epi::F32OUT ? Rf : Rw) : R, Rb1 = Epi::PERM ? (Epi::F32OUT ? Rf + 32 : Rw + 8) : R + HALF;
;         voffA[i] = (unsigned)(R * K + C) * 2u; voffB0[i] = (unsigned)(Rb0 * K + C) * 2u; voffB1[i] = (unsigned)(Rb1 * K + C) * 2u; }
;     const size_t kstep = (size_t)(BK * 2);
;     const size_t hstep = (size_t)HALF * K * 2;
;     const size_t tstep = 2 * hstep;
;     const unsigned ldsw = (unsigned)wid * 1024u;
;     const int aoff = lds_byte(wr * 64 + fr, fq * 8), boff = lds_byte(wc * 32 + fr, fq * 8);
;     ...
;     Unit cur, nxt; int ui = 0;
;     if (!S.next(0, cur)) return;
;     f32x4 acc[2][2][4][2];
; #pragma unroll
;     for (int a = 0; a < 2; ++a)
; #pragma unroll
;         for (int b = 0; b < 2; ++b)
; #pragma unroll
;             for (int m = 0; m < 4; ++m)
; #pragma unroll
;                 for (int n = 0; n < 2; ++n) acc[a][b][m][n] = (f32x4){0.f, 0.f, 0.f, 0.f};
;     bf16x8 At[4][2], B0[2][2], B1[2][2];
;     const char* cA = (const char*)g.A + (size_t)cur.pm * tstep; const char* cB = (const char*)g.Bt + (size_t)cur.pn * tstep;
;     PG8_STAGE(PG8_SB(0, 0), cB, voffB0); PG8_STAGE(PG8_SA(0, 0), cA, voffA); PG8_STAGE(PG8_SB(0, 1), cB, voffB1); PG8_STAGE(PG8_SA(0, 1), cA + hstep, voffA);
;     if (wr == 1) PG8_BAR;
;     PG8_WAIT_V(4); PG8_BAR;
;     PG8_STAGE(PG8_SB(1, 0), cB + kstep, voffB0); PG8_STAGE(PG8_SA(1, 0), cA + kstep, voffA); PG8_STAGE(PG8_SB(1, 1), cB + kstep, voffB1);
;     PG8_WAIT_V(6); PG8_BAR;
.LBB0_1592:
	v_ashrrev_i32_e32 v1, 31, v202
	v_lshrrev_b32_e32 v1, 26, v1
	v_add_u32_e32 v1, v202, v1
	v_ashrrev_i32_e32 v12, 6, v1
	v_bfe_i32 v1, v202, 27, 1
	v_lshlrev_b32_e32 v0, 4, v202
	v_lshrrev_b32_e32 v1, 22, v1
	v_add_u32_e32 v1, v0, v1
	v_and_b32_e32 v1, 0xfffffc00, v1
	v_sub_u32_e32 v1, v0, v1
	v_lshrrev_b32_e32 v2, 4, v1
	v_bitop3_b32 v1, v2, v1, 32 bitop3:0x6c
	v_ashrrev_i32_e32 v3, 31, v1
	v_lshrrev_b32_e32 v3, 26, v3
	v_add_u32_e32 v3, v1, v3
	v_lshlrev_b32_e32 v2, 3, v12
	v_ashrrev_i32_e32 v13, 6, v3
	v_and_b32_e32 v3, 0xc0, v3
	s_waitcnt lgkmcnt(0)
	s_add_u32 s8, s6, 0x6400000
	v_and_b32_e32 v2, -16, v2
	v_sub_u32_e32 v1, v1, v3
	v_mov_b32_e32 v3, 1
	s_addc_u32 s9, s7, 0
	v_add_u32_e32 v2, v13, v2
	v_ashrrev_i16_sdwa v1, v3, sext(v1) dst_sel:DWORD dst_unused:UNUSED_PAD src0_sel:DWORD src1_sel:BYTE_0
	s_add_u32 s33, s6, 0x1f000000
	v_lshlrev_b32_e32 v4, 5, v12
	v_bfe_i32 v14, v1, 0, 16
	v_lshlrev_b32_e32 v1, 1, v2
	v_lshrrev_b32_e32 v5, 2, v2
	s_addc_u32 s40, s7, 0
	v_and_b32_e32 v4, 32, v4
	v_and_b32_e32 v5, 4, v5
	v_and_b32_e32 v6, 3, v13
	v_and_b32_e32 v1, 0xfffd8, v1
	s_add_i32 s0, s10, s0
	v_or3_b32 v1, v6, v5, v1
	v_add_lshl_u32 v4, v4, v14, 1
	v_add_u32_e32 v0, 0x2000, v0
	s_ashr_i32 s10, s0, 31
	v_lshl_add_u32 v146, v1, 12, v4
	v_ashrrev_i32_e32 v1, 31, v0
	s_lshr_b32 s10, s10, 26
	v_lshrrev_b32_e32 v1, 22, v1
	s_add_i32 s10, s0, s10
	v_add_u32_e32 v1, v0, v1
	s_ashr_i32 s11, s10, 6
	s_and_b32 s10, s10, 0xffc0
	v_ashrrev_i32_e32 v15, 10, v1
	s_sub_i32 s10, s0, s10
	v_mul_i32_i24_e32 v1, 0x400, v15
	s_bfe_i32 s0, s10, 0x80000
	v_sub_u32_e32 v0, v0, v1
	s_bfe_u32 s0, s0, 0x3000c
	v_lshrrev_b32_e32 v1, 4, v0
	s_add_i32 s14, s10, s0
	v_bitop3_b32 v0, v1, v0, 32 bitop3:0x6c
	s_bfe_i32 s0, s14, 0x80000
	s_and_b32 s14, s14, 0xf8
	v_lshl_add_u32 v144, v2, 12, v4
	v_ashrrev_i32_e32 v2, 31, v0
	s_sub_i32 s10, s10, s14
	v_lshrrev_b32_e32 v2, 26, v2
	s_lshl_b32 s11, s11, 3
	s_sext_i32_i16 s0, s0
	s_sext_i32_i8 s10, s10
	s_ashr_i32 s1, s3, 6
	v_add_u32_e32 v2, v0, v2
	s_lshr_b32 s0, s0, 3
	s_add_i32 s30, s11, s10
	v_lshlrev_b32_e32 v1, 3, v15
	v_ashrrev_i32_e32 v16, 6, v2
	v_and_b32_e32 v2, 0xc0, v2
	s_ashr_i32 s31, s30, 31
	s_bfe_i64 s[14:15], s[0:1], 0x100000
	v_and_b32_e32 v1, -16, v1
	v_sub_u32_e32 v0, v0, v2
	s_ashr_i32 s16, s3, 8
	s_lshl_b32 s41, s1, 10
	s_lshl_b64 s[10:11], s[30:31], 20
	s_lshl_b64 s[14:15], s[14:15], 20
	v_add_u32_e32 v1, v16, v1
	v_ashrrev_i16_sdwa v0, v3, sext(v0) dst_sel:DWORD dst_unused:UNUSED_PAD src0_sel:DWORD src1_sel:BYTE_0
	s_add_u32 s36, s33, s14
	v_lshlrev_b32_e32 v4, 5, v15
	v_bfe_i32 v17, v0, 0, 16
	v_lshlrev_b32_e32 v0, 1, v1
	v_lshrrev_b32_e32 v2, 2, v1
	s_addc_u32 s37, s40, s15
	s_add_i32 s31, s41, 0
	v_and_b32_e32 v4, 32, v4
	v_and_b32_e32 v2, 4, v2
	v_and_b32_e32 v3, 3, v16
	v_and_b32_e32 v0, 0xfffd8, v0
	s_add_i32 m0, s31, 0x10000
	v_or3_b32 v0, v3, v2, v0
	v_add_lshl_u32 v2, v4, v17, 1
	global_load_lds_dwordx4 v146, s[36:37]
	s_add_i32 m0, s31, 0x12000
	v_lshl_add_u32 v152, v0, 12, v2
	s_add_u32 s34, s8, s10
	global_load_lds_dwordx4 v152, s[36:37]
	s_addc_u32 s35, s9, s11
	s_mov_b32 m0, s31
	s_add_i32 s42, s31, 0x2000
	v_lshl_add_u32 v150, v1, 12, v2
	global_load_lds_dwordx4 v144, s[34:35]
	s_mov_b32 m0, s42
	v_add_u32_e32 v148, 0x20000, v146
	global_load_lds_dwordx4 v150, s[34:35]
	s_add_i32 m0, s31, 0x14000
	v_add_u32_e32 v154, 0x20000, v152
	global_load_lds_dwordx4 v148, s[36:37]
	s_add_i32 m0, s31, 0x16000
	s_add_u32 s10, s34, 0x80000
	s_addc_u32 s11, s35, 0
	s_add_i32 s43, s31, 0x4000
	global_load_lds_dwordx4 v154, s[36:37]
	s_mov_b32 m0, s43
	s_add_i32 s44, s31, 0x6000
	global_load_lds_dwordx4 v144, s[10:11]
	s_mov_b32 m0, s44
	v_mov_b32_e32 v157, 0
	global_load_lds_dwordx4 v150, s[10:11]
	v_mov_b32_e32 v147, v157
	v_mov_b32_e32 v153, v157
	v_mov_b32_e32 v145, v157
	v_mov_b32_e32 v151, v157
	v_mov_b32_e32 v149, v157
	v_mov_b32_e32 v155, v157
	s_mov_b32 s46, 0
	s_mov_b32 s45, 0x10000
	v_lshl_add_u64 v[10:11], s[36:37], 0, v[146:147]
	v_lshl_add_u64 v[8:9], s[36:37], 0, v[152:153]
	v_lshl_add_u64 v[6:7], s[34:35], 0, v[144:145]
	v_lshl_add_u64 v[4:5], s[34:35], 0, v[150:151]
	v_lshl_add_u64 v[0:1], s[36:37], 0, v[148:149]
	s_cmp_lg_u32 s16, 1
	v_lshl_add_u64 v[2:3], s[36:37], 0, v[154:155]
	s_setprio 1
	s_cbranch_scc1 .LBB0_1594
	s_barrier
	s_setprio 0
